# GEMM main loops: M0 values formed directly from the wave LDS offset plus constant, B-operand ds_reads use one persistent base VGPR with immediate offsets (no per-phase v_add_u32 / SGPR chains)
# speedup vs baseline: 1.0212x; 1.0061x over previous
; __device__ __forceinline__ int prow0(int pm) { return (pm >> 4) * LP + PADR + (pm & 15) * 256; }
; template <class Epi>
; __device__ __forceinline__ void gemm_phase(LAS unsigned char* lds, const bf16_t* Ag, const bf16_t* Btg, const int K, const int nM, const int nN, const Epi& E) {
;     ...
;         const int un = u + G; const bool has_next = un < nunits; const int pmn = has_next ? un % nM : pm, pnn = has_next ? un / nM : pn;
;         const char* nA = has_next ? (const char*)Ag + (size_t)prow0(pmn) * rstep : cA; const char* nB = has_next ? (const char*)Btg + (size_t)pnn * tstep : cB;
.LBB0_72:
	v_add_u32_e32 v217, 0x10000, v175
	s_add_i32 s65, s65, s13
	s_cmpk_gt_i32 s65, 0x3ff
	s_cselect_b64 s[48:49], -1, 0
	s_cmpk_lt_i32 s65, 0x400
	s_cselect_b64 s[40:41], -1, 0
	s_ashr_i32 s12, s65, 31
	s_lshr_b32 s12, s12, 26
	s_add_i32 s12, s65, s12
	s_and_b32 s14, s12, 0xffffffc0
	s_sub_i32 s67, s65, s14
	s_lshl_b32 s14, s67, 8
	s_and_b32 s26, s14, 0xf00
	s_mov_b64 s[14:15], -1
	s_and_b64 vcc, exec, s[40:41]
	s_cbranch_vccz .LBB0_74
	s_lshr_b32 s14, s67, 4
	s_mulk_i32 s14, 0x1040
	s_add_i32 s14, s26, s14
	s_add_i32 s46, s14, 48
	s_ashr_i32 s47, s46, 31
	s_lshl_b64 s[14:15], s[46:47], 11
	s_add_u32 s42, s36, s14
	s_addc_u32 s43, s37, s15
	s_mov_b64 s[14:15], 0

;     __device__ __forceinline__ void prep(int pm, int par, LAS unsigned char* lds) const { if (fold) prep_rowstats(stat, pm, par, lds); }
;     __device__ __forceinline__ void prep(int pm, int par, LAS unsigned char* lds) const { if (!ident) prep_rowstats(stat, pm, par, lds); }
;     __device__ __forceinline__ void prep(int pm, int par, LAS unsigned char* lds) const { prep_rowstats(stat, pm, par, lds); }
; #define G_STAGE(bufoff, gbase) do { _Pragma("unroll") for (int _i = 0; _i < 2; ++_i) \
;         __builtin_amdgcn_global_load_lds((const unsigned*)((const char*)(gbase) + voff[_i]), (LAS unsigned*)(lds + (bufoff) + ldsw + _i * 8192), 16, 0, 0); } while (0)
; #define G_LDA(dst, b, h) do { _Pragma("unroll") for (int m = 0; m < 4; ++m) _Pragma("unroll") for (int k = 0; k < 2; ++k) dst[m][k] = *(const LAS bf16x8*)(lds + G_SA(b, h) + aoff + m * 2048 + k * 1024); } while (0)
; #define G_LDB(dst, b, h) do { _Pragma("unroll") for (int n = 0; n < 2; ++n) _Pragma("unroll") for (int k = 0; k < 2; ++k) dst[n][k] = *(const LAS bf16x8*)(lds + G_SB(b, h) + boff + n * 2048 + k * 1024); } while (0)
; #define G_WAIT_L(n) asm volatile("s_waitcnt lgkmcnt(" #n ")" ::: "memory")
; #define G_BAR __builtin_amdgcn_s_barrier()
; #define G_SCHED __builtin_amdgcn_sched_barrier(0)
; template <class Epi>
; __device__ __forceinline__ void gemm_phase(LAS unsigned char* lds, const bf16_t* Ag, const bf16_t* Btg, const int K, const int nM, const int nN, const Epi& E) {
;     ...
;         for (int t = 0; t < nt; t += 2) {
;             const bool last = (t == nt - 2);
;             const char* a1 = cA + (size_t)(t + 1) * kstep;
;             const char* a2 = last ? nA : cA + (size_t)(t + 2) * kstep; const char* b2 = last ? nB : cB + (size_t)(t + 2) * kstep;
;             const char* a3 = a2 + kstep; const char* b3 = b2 + kstep;
;             if (last && has_next && pmn != pm) E.prep(pmn, par ^ 1, lds);
;             G_LDB(B0, 0, 0); G_SCHED; G_LDA(At, 0, 0); G_STAGE(G_SA(1, 1), a1 + hstep);
;             G_WAIT_L(8); G_BAR; G_WAIT_L(0); G_MMA(0, 0, At, B0); G_BAR; G_SCHED;
;             G_LDB(B1, 0, 1); G_STAGE(G_SB(0, 0), b2);
;             G_BAR; G_WAIT_L(0); G_MMA(0, 1, At, B1); G_BAR;
;             G_LDA(At, 0, 1); G_STAGE(G_SA(0, 0), a2);
;             G_BAR; G_WAIT_L(0); G_MMA(1, 0, At, B0); G_BAR; G_SCHED;
;             G_STAGE(G_SB(0, 1), b2 + hstep);
.LBB0_78:
	s_add_u32 s12, s50, 0xfffc0080
	s_addc_u32 s26, s51, -1
	s_and_b64 s[52:53], s[52:53], exec
	s_cselect_b32 s55, s26, s43
	s_cselect_b32 s54, s12, s42
	s_cselect_b32 s53, s72, s15
	s_cselect_b32 s52, s71, s69
	ds_read_b128 v[124:127], v217
	ds_read_b128 v[128:131], v217 offset:1024
	ds_read_b128 v[132:135], v217 offset:2048
	ds_read_b128 v[136:139], v217 offset:3072
	s_add_i32 m0, s58, 0xc000
	ds_read_b128 v[140:143], v186
	ds_read_b128 v[148:151], v186 offset:1024
	ds_read_b128 v[152:155], v186 offset:2048
	ds_read_b128 v[156:159], v186 offset:3072
	ds_read_b128 v[188:191], v186 offset:4096
	ds_read_b128 v[192:195], v186 offset:5120
	ds_read_b128 v[222:225], v186 offset:6144
	global_load_lds_dwordx4 v170, s[50:51]
	s_add_i32 m0, s58, 0xe000
	ds_read_b128 v[226:229], v186 offset:7168
	global_load_lds_dwordx4 v168, s[50:51]
	s_waitcnt lgkmcnt(8)
	s_barrier
	s_waitcnt lgkmcnt(0)
	s_setprio 1
	s_waitcnt lgkmcnt(0)
	v_mfma_f32_16x16x32_bf16 v[164:167], v[124:127], v[140:143], v[164:167]
	v_mfma_f32_16x16x32_bf16 v[160:163], v[132:135], v[140:143], v[160:163]
	v_mfma_f32_16x16x32_bf16 v[116:119], v[124:127], v[152:155], v[116:119]
	v_mfma_f32_16x16x32_bf16 v[112:115], v[132:135], v[152:155], v[112:115]
	v_mfma_f32_16x16x32_bf16 v[100:103], v[124:127], v[188:191], v[100:103]
	v_mfma_f32_16x16x32_bf16 v[96:99], v[132:135], v[188:191], v[96:99]
	v_mfma_f32_16x16x32_bf16 v[84:87], v[124:127], v[222:225], v[84:87]
	v_mfma_f32_16x16x32_bf16 v[80:83], v[132:135], v[222:225], v[80:83]
	v_mfma_f32_16x16x32_bf16 v[164:167], v[128:131], v[148:151], v[164:167]
	v_mfma_f32_16x16x32_bf16 v[160:163], v[136:139], v[148:151], v[160:163]
	v_mfma_f32_16x16x32_bf16 v[116:119], v[128:131], v[156:159], v[116:119]
	v_mfma_f32_16x16x32_bf16 v[112:115], v[136:139], v[156:159], v[112:115]
	v_mfma_f32_16x16x32_bf16 v[100:103], v[128:131], v[192:195], v[100:103]
	v_mfma_f32_16x16x32_bf16 v[96:99], v[136:139], v[192:195], v[96:99]
	v_mfma_f32_16x16x32_bf16 v[84:87], v[128:131], v[226:229], v[84:87]
	v_mfma_f32_16x16x32_bf16 v[80:83], v[136:139], v[226:229], v[80:83]
	s_setprio 0
	s_barrier
	ds_read_b128 v[230:233], v217 offset:16384
	ds_read_b128 v[234:237], v217 offset:17408
	s_add_i32 m0, s57, 0x10000
	ds_read_b128 v[238:241], v217 offset:18432
	global_load_lds_dwordx4 v0, s[52:53]
	s_add_i32 m0, s57, 0x12000
	ds_read_b128 v[242:245], v217 offset:19456
	global_load_lds_dwordx4 v2, s[52:53]
	s_barrier
	s_waitcnt lgkmcnt(0)
	s_setprio 1
	s_waitcnt lgkmcnt(0)
	v_mfma_f32_16x16x32_bf16 v[144:147], v[230:233], v[140:143], v[144:147]
	v_mfma_f32_16x16x32_bf16 v[120:123], v[238:241], v[140:143], v[120:123]
	v_mfma_f32_16x16x32_bf16 v[108:111], v[230:233], v[152:155], v[108:111]
	v_mfma_f32_16x16x32_bf16 v[104:107], v[238:241], v[152:155], v[104:107]
	v_mfma_f32_16x16x32_bf16 v[92:95], v[230:233], v[188:191], v[92:95]
	v_mfma_f32_16x16x32_bf16 v[88:91], v[238:241], v[188:191], v[88:91]
	v_mfma_f32_16x16x32_bf16 v[76:79], v[230:233], v[222:225], v[76:79]
	v_mfma_f32_16x16x32_bf16 v[72:75], v[238:241], v[222:225], v[72:75]
	v_mfma_f32_16x16x32_bf16 v[144:147], v[234:237], v[148:151], v[144:147]
	v_mfma_f32_16x16x32_bf16 v[120:123], v[242:245], v[148:151], v[120:123]
	v_mfma_f32_16x16x32_bf16 v[108:111], v[234:237], v[156:159], v[108:111]
	v_mfma_f32_16x16x32_bf16 v[104:107], v[242:245], v[156:159], v[104:107]
	v_mfma_f32_16x16x32_bf16 v[92:95], v[234:237], v[192:195], v[92:95]
	v_mfma_f32_16x16x32_bf16 v[88:91], v[242:245], v[192:195], v[88:91]
	v_mfma_f32_16x16x32_bf16 v[76:79], v[234:237], v[226:229], v[76:79]
	v_mfma_f32_16x16x32_bf16 v[72:75], v[242:245], v[226:229], v[72:75]
	s_setprio 0
	s_mov_b32 m0, s58
	s_barrier
	ds_read_b128 v[140:143], v186 offset:16384
	ds_read_b128 v[148:151], v186 offset:17408
	ds_read_b128 v[152:155], v186 offset:18432
	ds_read_b128 v[156:159], v186 offset:19456
	ds_read_b128 v[188:191], v186 offset:20480
	ds_read_b128 v[192:195], v186 offset:21504
	ds_read_b128 v[222:225], v186 offset:22528
	global_load_lds_dwordx4 v0, s[54:55]
	s_mov_b32 m0, s59
	ds_read_b128 v[226:229], v186 offset:23552
	global_load_lds_dwordx4 v2, s[54:55]
	s_barrier
	s_waitcnt lgkmcnt(0)
	s_setprio 1
	s_waitcnt lgkmcnt(0)
	v_mfma_f32_16x16x32_bf16 v[60:63], v[124:127], v[140:143], v[60:63]
	v_mfma_f32_16x16x32_bf16 v[56:59], v[132:135], v[140:143], v[56:59]
	v_mfma_f32_16x16x32_bf16 v[44:47], v[124:127], v[152:155], v[44:47]
	v_mfma_f32_16x16x32_bf16 v[40:43], v[132:135], v[152:155], v[40:43]
	v_mfma_f32_16x16x32_bf16 v[28:31], v[124:127], v[188:191], v[28:31]
	v_mfma_f32_16x16x32_bf16 v[24:27], v[132:135], v[188:191], v[24:27]
	v_mfma_f32_16x16x32_bf16 v[12:15], v[124:127], v[222:225], v[12:15]
	v_mfma_f32_16x16x32_bf16 v[8:11], v[132:135], v[222:225], v[8:11]
	v_mfma_f32_16x16x32_bf16 v[60:63], v[128:131], v[148:151], v[60:63]
	v_mfma_f32_16x16x32_bf16 v[56:59], v[136:139], v[148:151], v[56:59]
	v_mfma_f32_16x16x32_bf16 v[44:47], v[128:131], v[156:159], v[44:47]
	v_mfma_f32_16x16x32_bf16 v[40:43], v[136:139], v[156:159], v[40:43]
	v_mfma_f32_16x16x32_bf16 v[28:31], v[128:131], v[192:195], v[28:31]
	v_mfma_f32_16x16x32_bf16 v[24:27], v[136:139], v[192:195], v[24:27]
	v_mfma_f32_16x16x32_bf16 v[12:15], v[128:131], v[226:229], v[12:15]
	v_mfma_f32_16x16x32_bf16 v[8:11], v[136:139], v[226:229], v[8:11]
	s_setprio 0
	s_barrier
	s_add_u32 s74, s52, 0x40000
	s_addc_u32 s75, s53, 0
	s_add_i32 m0, s57, 0x14000
	s_nop 0
	global_load_lds_dwordx4 v0, s[74:75]
	s_add_i32 m0, s57, 0x16000
	s_nop 0
	global_load_lds_dwordx4 v2, s[74:75]
	s_waitcnt vmcnt(6)
	s_barrier
; #define G_STAGE(bufoff, gbase) do { _Pragma("unroll") for (int _i = 0; _i < 2; ++_i) \
;         __builtin_amdgcn_global_load_lds((const unsigned*)((const char*)(gbase) + voff[_i]), (LAS unsigned*)(lds + (bufoff) + ldsw + _i * 8192), 16, 0, 0); } while (0)
; #define G_LDA(dst, b, h) do { _Pragma("unroll") for (int m = 0; m < 4; ++m) _Pragma("unroll") for (int k = 0; k < 2; ++k) dst[m][k] = *(const LAS bf16x8*)(lds + G_SA(b, h) + aoff + m * 2048 + k * 1024); } while (0)
; #define G_LDB(dst, b, h) do { _Pragma("unroll") for (int n = 0; n < 2; ++n) _Pragma("unroll") for (int k = 0; k < 2; ++k) dst[n][k] = *(const LAS bf16x8*)(lds + G_SB(b, h) + boff + n * 2048 + k * 1024); } while (0)
; #define G_MMA(ai, bj, At, Bt) do { __builtin_amdgcn_s_setprio(1); _Pragma("unroll") for (int m = 0; m < 4; ++m) _Pragma("unroll") for (int n = 0; n < 2; ++n) _Pragma("unroll") for (int k = 0; k < 2; ++k) \
;         acc[ai][bj][m][n] = MFMA16(Bt[n][k], At[m][k], acc[ai][bj][m][n]); __builtin_amdgcn_s_setprio(0); } while (0)
; #define G_WAIT_V(n) asm volatile("s_waitcnt vmcnt(" #n ")" ::: "memory")
; #define G_WAIT_L(n) asm volatile("s_waitcnt lgkmcnt(" #n ")" ::: "memory")
; #define G_BAR __builtin_amdgcn_s_barrier()
; #define G_SCHED __builtin_amdgcn_sched_barrier(0)
; template <class Epi>
; __device__ __forceinline__ void gemm_phase(LAS unsigned char* lds, const bf16_t* Ag, const bf16_t* Btg, const int K, const int nM, const int nN, const Epi& E) {
;     ...
;             G_WAIT_V(6); G_BAR; G_MMA(1, 1, At, B1); G_BAR;
;             G_LDB(B0, 1, 0); G_SCHED; G_LDA(At, 1, 0); G_STAGE(G_SA(0, 1), a2 + hstep);
;             G_WAIT_L(8); G_BAR; G_WAIT_L(0); G_MMA(0, 0, At, B0); G_BAR; G_SCHED;
;             G_LDB(B1, 1, 1); G_STAGE(G_SB(1, 0), b3);
	s_setprio 1
	v_mfma_f32_16x16x32_bf16 v[68:71], v[230:233], v[140:143], v[68:71]
	v_mfma_f32_16x16x32_bf16 v[64:67], v[238:241], v[140:143], v[64:67]
	v_mfma_f32_16x16x32_bf16 v[52:55], v[230:233], v[152:155], v[52:55]
	v_mfma_f32_16x16x32_bf16 v[48:51], v[238:241], v[152:155], v[48:51]
	v_mfma_f32_16x16x32_bf16 v[36:39], v[230:233], v[188:191], v[36:39]
	v_mfma_f32_16x16x32_bf16 v[32:35], v[238:241], v[188:191], v[32:35]
	v_mfma_f32_16x16x32_bf16 v[20:23], v[230:233], v[222:225], v[20:23]
	v_mfma_f32_16x16x32_bf16 v[16:19], v[238:241], v[222:225], v[16:19]
	v_mfma_f32_16x16x32_bf16 v[68:71], v[234:237], v[148:151], v[68:71]
	v_mfma_f32_16x16x32_bf16 v[64:67], v[242:245], v[148:151], v[64:67]
	v_mfma_f32_16x16x32_bf16 v[52:55], v[234:237], v[156:159], v[52:55]
	v_mfma_f32_16x16x32_bf16 v[48:51], v[242:245], v[156:159], v[48:51]
	v_mfma_f32_16x16x32_bf16 v[36:39], v[234:237], v[192:195], v[36:39]
	v_mfma_f32_16x16x32_bf16 v[32:35], v[242:245], v[192:195], v[32:35]
	v_mfma_f32_16x16x32_bf16 v[20:23], v[234:237], v[226:229], v[20:23]
	v_mfma_f32_16x16x32_bf16 v[16:19], v[242:245], v[226:229], v[16:19]
	s_setprio 0
	s_barrier
	ds_read_b128 v[124:127], v217 offset:32768
	ds_read_b128 v[128:131], v217 offset:33792
	ds_read_b128 v[132:135], v217 offset:34816
	ds_read_b128 v[136:139], v217 offset:35840
	s_add_u32 s54, s54, 0x40000
	s_addc_u32 s55, s55, 0
	s_mov_b32 m0, s60
	ds_read_b128 v[140:143], v186 offset:32768
	ds_read_b128 v[148:151], v186 offset:33792
	ds_read_b128 v[152:155], v186 offset:34816
	ds_read_b128 v[156:159], v186 offset:35840
	ds_read_b128 v[188:191], v186 offset:36864
	ds_read_b128 v[192:195], v186 offset:37888
	ds_read_b128 v[222:225], v186 offset:38912
	global_load_lds_dwordx4 v0, s[54:55]
	s_mov_b32 m0, s61
	ds_read_b128 v[226:229], v186 offset:39936
	global_load_lds_dwordx4 v2, s[54:55]
	s_waitcnt lgkmcnt(8)
	s_barrier
	s_waitcnt lgkmcnt(0)
	s_setprio 1
	s_waitcnt lgkmcnt(0)
	v_mfma_f32_16x16x32_bf16 v[164:167], v[124:127], v[140:143], v[164:167]
	v_mfma_f32_16x16x32_bf16 v[160:163], v[132:135], v[140:143], v[160:163]
	v_mfma_f32_16x16x32_bf16 v[116:119], v[124:127], v[152:155], v[116:119]
	v_mfma_f32_16x16x32_bf16 v[112:115], v[132:135], v[152:155], v[112:115]
	v_mfma_f32_16x16x32_bf16 v[100:103], v[124:127], v[188:191], v[100:103]
	v_mfma_f32_16x16x32_bf16 v[96:99], v[132:135], v[188:191], v[96:99]
	v_mfma_f32_16x16x32_bf16 v[84:87], v[124:127], v[222:225], v[84:87]
	v_mfma_f32_16x16x32_bf16 v[80:83], v[132:135], v[222:225], v[80:83]
	v_mfma_f32_16x16x32_bf16 v[164:167], v[128:131], v[148:151], v[164:167]
	v_mfma_f32_16x16x32_bf16 v[160:163], v[136:139], v[148:151], v[160:163]
	v_mfma_f32_16x16x32_bf16 v[116:119], v[128:131], v[156:159], v[116:119]
	v_mfma_f32_16x16x32_bf16 v[112:115], v[136:139], v[156:159], v[112:115]
	v_mfma_f32_16x16x32_bf16 v[100:103], v[128:131], v[192:195], v[100:103]
	v_mfma_f32_16x16x32_bf16 v[96:99], v[136:139], v[192:195], v[96:99]
	v_mfma_f32_16x16x32_bf16 v[84:87], v[128:131], v[226:229], v[84:87]
	v_mfma_f32_16x16x32_bf16 v[80:83], v[136:139], v[226:229], v[80:83]
	s_setprio 0
	s_barrier
	s_add_i32 s26, 0, 0x1c000
	s_add_i32 m0, s57, 0x18000
	ds_read_b128 v[230:233], v217 offset:49152
	ds_read_b128 v[234:237], v217 offset:50176
	ds_read_b128 v[238:241], v217 offset:51200
	ds_read_b128 v[242:245], v217 offset:52224
	s_add_u32 s98, s52, 0x80
	s_addc_u32 s99, s53, 0
	global_load_lds_dwordx4 v0, s[98:99]
	s_add_i32 m0, s57, 0x1a000
	s_nop 0
	global_load_lds_dwordx4 v2, s[98:99]
	s_barrier
; #define G_STAGE(bufoff, gbase) do { _Pragma("unroll") for (int _i = 0; _i < 2; ++_i) \
;         __builtin_amdgcn_global_load_lds((const unsigned*)((const char*)(gbase) + voff[_i]), (LAS unsigned*)(lds + (bufoff) + ldsw + _i * 8192), 16, 0, 0); } while (0)
; #define G_LDA(dst, b, h) do { _Pragma("unroll") for (int m = 0; m < 4; ++m) _Pragma("unroll") for (int k = 0; k < 2; ++k) dst[m][k] = *(const LAS bf16x8*)(lds + G_SA(b, h) + aoff + m * 2048 + k * 1024); } while (0)
; #define G_MMA(ai, bj, At, Bt) do { __builtin_amdgcn_s_setprio(1); _Pragma("unroll") for (int m = 0; m < 4; ++m) _Pragma("unroll") for (int n = 0; n < 2; ++n) _Pragma("unroll") for (int k = 0; k < 2; ++k) \
;         acc[ai][bj][m][n] = MFMA16(Bt[n][k], At[m][k], acc[ai][bj][m][n]); __builtin_amdgcn_s_setprio(0); } while (0)
; #define G_WAIT_V(n) asm volatile("s_waitcnt vmcnt(" #n ")" ::: "memory")
; #define G_WAIT_L(n) asm volatile("s_waitcnt lgkmcnt(" #n ")" ::: "memory")
; #define G_BAR __builtin_amdgcn_s_barrier()
; #define G_SCHED __builtin_amdgcn_sched_barrier(0)
; template <class Epi>
; __device__ __forceinline__ void gemm_phase(LAS unsigned char* lds, const bf16_t* Ag, const bf16_t* Btg, const int K, const int nM, const int nN, const Epi& E) {
;     ...
;         for (int t = 0; t < nt; t += 2) {
;     ...
;             G_BAR; G_WAIT_L(0); G_MMA(0, 1, At, B1); G_BAR;
;             G_LDA(At, 1, 1); G_STAGE(G_SA(1, 0), a3);
;             G_BAR; G_WAIT_L(0); G_MMA(1, 0, At, B0); G_BAR; G_SCHED;
;             G_STAGE(G_SB(1, 1), b3 + hstep);
;             G_WAIT_V(6); G_BAR; G_MMA(1, 1, At, B1); G_BAR;
	s_waitcnt lgkmcnt(0)
	s_setprio 1
	s_waitcnt lgkmcnt(0)
	v_mfma_f32_16x16x32_bf16 v[144:147], v[230:233], v[140:143], v[144:147]
	v_mfma_f32_16x16x32_bf16 v[120:123], v[238:241], v[140:143], v[120:123]
	v_mfma_f32_16x16x32_bf16 v[108:111], v[230:233], v[152:155], v[108:111]
	v_mfma_f32_16x16x32_bf16 v[104:107], v[238:241], v[152:155], v[104:107]
	v_mfma_f32_16x16x32_bf16 v[92:95], v[230:233], v[188:191], v[92:95]
	v_mfma_f32_16x16x32_bf16 v[88:91], v[238:241], v[188:191], v[88:91]
	v_mfma_f32_16x16x32_bf16 v[76:79], v[230:233], v[222:225], v[76:79]
	v_mfma_f32_16x16x32_bf16 v[72:75], v[238:241], v[222:225], v[72:75]
	v_mfma_f32_16x16x32_bf16 v[144:147], v[234:237], v[148:151], v[144:147]
	v_mfma_f32_16x16x32_bf16 v[120:123], v[242:245], v[148:151], v[120:123]
	v_mfma_f32_16x16x32_bf16 v[108:111], v[234:237], v[156:159], v[108:111]
	v_mfma_f32_16x16x32_bf16 v[104:107], v[242:245], v[156:159], v[104:107]
	v_mfma_f32_16x16x32_bf16 v[92:95], v[234:237], v[192:195], v[92:95]
	v_mfma_f32_16x16x32_bf16 v[88:91], v[242:245], v[192:195], v[88:91]
	v_mfma_f32_16x16x32_bf16 v[76:79], v[234:237], v[226:229], v[76:79]
	v_mfma_f32_16x16x32_bf16 v[72:75], v[242:245], v[226:229], v[72:75]
	s_setprio 0
	s_mov_b32 m0, s62
	s_barrier
	ds_read_b128 v[140:143], v186 offset:49152
	ds_read_b128 v[148:151], v186 offset:50176
	ds_read_b128 v[152:155], v186 offset:51200
	ds_read_b128 v[156:159], v186 offset:52224
	ds_read_b128 v[188:191], v186 offset:53248
	ds_read_b128 v[192:195], v186 offset:54272
	ds_read_b128 v[222:225], v186 offset:55296
	ds_read_b128 v[226:229], v186 offset:56320
	s_add_u32 s98, s54, 0xfffc0080
	s_addc_u32 s99, s55, -1
	global_load_lds_dwordx4 v0, s[98:99]
	s_mov_b32 m0, s63
	s_nop 0
	global_load_lds_dwordx4 v2, s[98:99]
	s_barrier
	s_waitcnt lgkmcnt(0)
	s_setprio 1
	s_waitcnt lgkmcnt(0)
	v_mfma_f32_16x16x32_bf16 v[60:63], v[124:127], v[140:143], v[60:63]
	v_mfma_f32_16x16x32_bf16 v[56:59], v[132:135], v[140:143], v[56:59]
	v_mfma_f32_16x16x32_bf16 v[44:47], v[124:127], v[152:155], v[44:47]
	v_mfma_f32_16x16x32_bf16 v[40:43], v[132:135], v[152:155], v[40:43]
	v_mfma_f32_16x16x32_bf16 v[28:31], v[124:127], v[188:191], v[28:31]
	v_mfma_f32_16x16x32_bf16 v[24:27], v[132:135], v[188:191], v[24:27]
	v_mfma_f32_16x16x32_bf16 v[12:15], v[124:127], v[222:225], v[12:15]
	v_mfma_f32_16x16x32_bf16 v[8:11], v[132:135], v[222:225], v[8:11]
	v_mfma_f32_16x16x32_bf16 v[60:63], v[128:131], v[148:151], v[60:63]
	v_mfma_f32_16x16x32_bf16 v[56:59], v[136:139], v[148:151], v[56:59]
	v_mfma_f32_16x16x32_bf16 v[44:47], v[128:131], v[156:159], v[44:47]
	v_mfma_f32_16x16x32_bf16 v[40:43], v[136:139], v[156:159], v[40:43]
	v_mfma_f32_16x16x32_bf16 v[28:31], v[128:131], v[192:195], v[28:31]
	v_mfma_f32_16x16x32_bf16 v[24:27], v[136:139], v[192:195], v[24:27]
	v_mfma_f32_16x16x32_bf16 v[12:15], v[128:131], v[226:229], v[12:15]
	v_mfma_f32_16x16x32_bf16 v[8:11], v[136:139], v[226:229], v[8:11]
	s_setprio 0
	s_barrier
	s_add_u32 s52, s52, 0x40080
	s_addc_u32 s53, s53, 0
	s_add_i32 s12, s26, s57
	s_add_i32 m0, s57, 0x1c000
	s_nop 0
	global_load_lds_dwordx4 v0, s[52:53]
	s_add_i32 m0, s57, 0x1e000
	s_nop 0
	global_load_lds_dwordx4 v2, s[52:53]
	s_waitcnt vmcnt(6)
	s_barrier
	s_setprio 1
	v_mfma_f32_16x16x32_bf16 v[68:71], v[230:233], v[140:143], v[68:71]
	v_mfma_f32_16x16x32_bf16 v[64:67], v[238:241], v[140:143], v[64:67]
	v_mfma_f32_16x16x32_bf16 v[52:55], v[230:233], v[152:155], v[52:55]
	v_mfma_f32_16x16x32_bf16 v[48:51], v[238:241], v[152:155], v[48:51]
	v_mfma_f32_16x16x32_bf16 v[36:39], v[230:233], v[188:191], v[36:39]
	v_mfma_f32_16x16x32_bf16 v[32:35], v[238:241], v[188:191], v[32:35]
	v_mfma_f32_16x16x32_bf16 v[20:23], v[230:233], v[222:225], v[20:23]
	v_mfma_f32_16x16x32_bf16 v[16:19], v[238:241], v[222:225], v[16:19]
	v_mfma_f32_16x16x32_bf16 v[68:71], v[234:237], v[148:151], v[68:71]
	v_mfma_f32_16x16x32_bf16 v[64:67], v[242:245], v[148:151], v[64:67]
	v_mfma_f32_16x16x32_bf16 v[52:55], v[234:237], v[156:159], v[52:55]
	v_mfma_f32_16x16x32_bf16 v[48:51], v[242:245], v[156:159], v[48:51]
	v_mfma_f32_16x16x32_bf16 v[36:39], v[234:237], v[192:195], v[36:39]
	v_mfma_f32_16x16x32_bf16 v[32:35], v[242:245], v[192:195], v[32:35]
	v_mfma_f32_16x16x32_bf16 v[20:23], v[234:237], v[226:229], v[20:23]
	v_mfma_f32_16x16x32_bf16 v[16:19], v[242:245], v[226:229], v[16:19]
	s_setprio 0
	s_add_i32 s73, s73, 2
	s_add_u32 s71, s71, 0x100
	s_addc_u32 s72, s72, 0
	s_add_u32 s50, s50, 0x100
	s_addc_u32 s51, s51, 0
	s_cmp_gt_u32 s73, 13
	s_barrier
	s_cbranch_scc1 .LBB0_82

; __device__ __forceinline__ int prow0(int pm) { return (pm >> 4) * LP + PADR + (pm & 15) * 256; }
; template <class Epi>
; __device__ __forceinline__ void gemm_phase(LAS unsigned char* lds, const bf16_t* Ag, const bf16_t* Btg, const int K, const int nM, const int nN, const Epi& E) {
;     ...
;         const int un = u + G; const bool has_next = un < nunits; const int pmn = has_next ? un % nM : pm, pnn = has_next ? un / nM : pn;
;         const char* nA = has_next ? (const char*)Ag + (size_t)prow0(pmn) * rstep : cA; const char* nB = has_next ? (const char*)Btg + (size_t)pnn * tstep : cB;
.LBB0_147:
	v_add_u32_e32 v217, 0x10000, v179
	s_add_i32 s78, s78, s13
	s_cmpk_gt_i32 s78, 0xff
	s_cselect_b64 s[62:63], -1, 0
	s_cmpk_lt_i32 s78, 0x100
	s_cselect_b64 s[52:53], -1, 0
	s_ashr_i32 s12, s78, 31
	s_lshr_b32 s12, s12, 26
	s_add_i32 s12, s78, s12
	s_and_b32 s14, s12, 0xffffffc0
	s_sub_i32 s79, s78, s14
	s_lshl_b32 s14, s79, 8
	s_and_b32 s26, s14, 0xf00
	s_mov_b64 s[14:15], -1
	s_and_b64 vcc, exec, s[52:53]
	s_cbranch_vccz .LBB0_149
	s_lshr_b32 s14, s79, 4
	s_mulk_i32 s14, 0x1040
	s_add_i32 s14, s26, s14
	s_add_i32 s60, s14, 48
	s_ashr_i32 s61, s60, 31
	s_lshl_b64 s[14:15], s[60:61], 11
	s_add_u32 s54, s50, s14
	s_addc_u32 s55, s51, s15
	s_mov_b64 s[14:15], 0

;     __device__ __forceinline__ void prep(int pm, int par, LAS unsigned char* lds) const { if (fold) prep_rowstats(stat, pm, par, lds); }
;     __device__ __forceinline__ void prep(int pm, int par, LAS unsigned char* lds) const { if (!ident) prep_rowstats(stat, pm, par, lds); }
;     __device__ __forceinline__ void prep(int pm, int par, LAS unsigned char* lds) const { prep_rowstats(stat, pm, par, lds); }
; #define G_STAGE(bufoff, gbase) do { _Pragma("unroll") for (int _i = 0; _i < 2; ++_i) \
;         __builtin_amdgcn_global_load_lds((const unsigned*)((const char*)(gbase) + voff[_i]), (LAS unsigned*)(lds + (bufoff) + ldsw + _i * 8192), 16, 0, 0); } while (0)
; #define G_LDA(dst, b, h) do { _Pragma("unroll") for (int m = 0; m < 4; ++m) _Pragma("unroll") for (int k = 0; k < 2; ++k) dst[m][k] = *(const LAS bf16x8*)(lds + G_SA(b, h) + aoff + m * 2048 + k * 1024); } while (0)
; #define G_LDB(dst, b, h) do { _Pragma("unroll") for (int n = 0; n < 2; ++n) _Pragma("unroll") for (int k = 0; k < 2; ++k) dst[n][k] = *(const LAS bf16x8*)(lds + G_SB(b, h) + boff + n * 2048 + k * 1024); } while (0)
; #define G_WAIT_L(n) asm volatile("s_waitcnt lgkmcnt(" #n ")" ::: "memory")
; #define G_BAR __builtin_amdgcn_s_barrier()
; #define G_SCHED __builtin_amdgcn_sched_barrier(0)
; template <class Epi>
; __device__ __forceinline__ void gemm_phase(LAS unsigned char* lds, const bf16_t* Ag, const bf16_t* Btg, const int K, const int nM, const int nN, const Epi& E) {
;     ...
;         for (int t = 0; t < nt; t += 2) {
;             const bool last = (t == nt - 2);
;             const char* a1 = cA + (size_t)(t + 1) * kstep;
;             const char* a2 = last ? nA : cA + (size_t)(t + 2) * kstep; const char* b2 = last ? nB : cB + (size_t)(t + 2) * kstep;
;             const char* a3 = a2 + kstep; const char* b3 = b2 + kstep;
;             if (last && has_next && pmn != pm) E.prep(pmn, par ^ 1, lds);
;             G_LDB(B0, 0, 0); G_SCHED; G_LDA(At, 0, 0); G_STAGE(G_SA(1, 1), a1 + hstep);
;             G_WAIT_L(8); G_BAR; G_WAIT_L(0); G_MMA(0, 0, At, B0); G_BAR; G_SCHED;
;             G_LDB(B1, 0, 1); G_STAGE(G_SB(0, 0), b2);
;             G_BAR; G_WAIT_L(0); G_MMA(0, 1, At, B1); G_BAR;
;             G_LDA(At, 0, 1); G_STAGE(G_SA(0, 0), a2);
;             G_BAR; G_WAIT_L(0); G_MMA(1, 0, At, B0); G_BAR; G_SCHED;
;             G_STAGE(G_SB(0, 1), b2 + hstep);
.LBB0_153:
	s_add_u32 s66, s64, 0x100
	s_addc_u32 s67, s65, 0
	s_and_b64 s[68:69], s[68:69], exec
	s_cselect_b32 s71, s67, s55
	s_cselect_b32 s70, s66, s54
	s_cselect_b32 s69, s61, s14
	s_cselect_b32 s68, s57, s15
	ds_read_b128 v[144:147], v217
	ds_read_b128 v[148:151], v217 offset:1024
	ds_read_b128 v[152:155], v217 offset:2048
	ds_read_b128 v[156:159], v217 offset:3072
	s_add_i32 m0, s72, 0xc000
	ds_read_b128 v[160:163], v230
	ds_read_b128 v[164:167], v230 offset:1024
	ds_read_b128 v[168:171], v230 offset:2048
	ds_read_b128 v[172:175], v230 offset:3072
	ds_read_b128 v[180:183], v230 offset:4096
	ds_read_b128 v[184:187], v230 offset:5120
	ds_read_b128 v[188:191], v230 offset:6144
	global_load_lds_dwordx4 v138, s[64:65]
	s_add_i32 m0, s72, 0xe000
	ds_read_b128 v[192:195], v230 offset:7168
	global_load_lds_dwordx4 v136, s[64:65]
	s_waitcnt lgkmcnt(8)
	s_barrier
	s_waitcnt lgkmcnt(0)
	s_setprio 1
	s_waitcnt lgkmcnt(0)
	v_mfma_f32_16x16x32_bf16 v[132:135], v[144:147], v[160:163], v[132:135]
	v_mfma_f32_16x16x32_bf16 v[128:131], v[152:155], v[160:163], v[128:131]
	v_mfma_f32_16x16x32_bf16 v[116:119], v[144:147], v[168:171], v[116:119]
	v_mfma_f32_16x16x32_bf16 v[112:115], v[152:155], v[168:171], v[112:115]
	v_mfma_f32_16x16x32_bf16 v[100:103], v[144:147], v[180:183], v[100:103]
	v_mfma_f32_16x16x32_bf16 v[96:99], v[152:155], v[180:183], v[96:99]
	v_mfma_f32_16x16x32_bf16 v[84:87], v[144:147], v[188:191], v[84:87]
	v_mfma_f32_16x16x32_bf16 v[80:83], v[152:155], v[188:191], v[80:83]
	v_mfma_f32_16x16x32_bf16 v[132:135], v[148:151], v[164:167], v[132:135]
	v_mfma_f32_16x16x32_bf16 v[128:131], v[156:159], v[164:167], v[128:131]
	v_mfma_f32_16x16x32_bf16 v[116:119], v[148:151], v[172:175], v[116:119]
	v_mfma_f32_16x16x32_bf16 v[112:115], v[156:159], v[172:175], v[112:115]
	v_mfma_f32_16x16x32_bf16 v[100:103], v[148:151], v[184:187], v[100:103]
	v_mfma_f32_16x16x32_bf16 v[96:99], v[156:159], v[184:187], v[96:99]
	v_mfma_f32_16x16x32_bf16 v[84:87], v[148:151], v[192:195], v[84:87]
	v_mfma_f32_16x16x32_bf16 v[80:83], v[156:159], v[192:195], v[80:83]
	s_setprio 0
	s_barrier
	s_add_i32 m0, s21, 0x10000
	ds_read_b128 v[232:235], v217 offset:16384
	ds_read_b128 v[236:239], v217 offset:17408
	ds_read_b128 v[240:243], v217 offset:18432
	global_load_lds_dwordx4 v0, s[68:69]
	s_add_i32 m0, s21, 0x12000
	ds_read_b128 v[244:247], v217 offset:19456
	global_load_lds_dwordx4 v2, s[68:69]
	s_barrier
	s_waitcnt lgkmcnt(0)
	s_setprio 1
	s_waitcnt lgkmcnt(0)
	v_mfma_f32_16x16x32_bf16 v[124:127], v[232:235], v[160:163], v[124:127]
	v_mfma_f32_16x16x32_bf16 v[120:123], v[240:243], v[160:163], v[120:123]
	v_mfma_f32_16x16x32_bf16 v[108:111], v[232:235], v[168:171], v[108:111]
	v_mfma_f32_16x16x32_bf16 v[104:107], v[240:243], v[168:171], v[104:107]
	v_mfma_f32_16x16x32_bf16 v[92:95], v[232:235], v[180:183], v[92:95]
	v_mfma_f32_16x16x32_bf16 v[88:91], v[240:243], v[180:183], v[88:91]
	v_mfma_f32_16x16x32_bf16 v[76:79], v[232:235], v[188:191], v[76:79]
	v_mfma_f32_16x16x32_bf16 v[72:75], v[240:243], v[188:191], v[72:75]
	v_mfma_f32_16x16x32_bf16 v[124:127], v[236:239], v[164:167], v[124:127]
	v_mfma_f32_16x16x32_bf16 v[120:123], v[244:247], v[164:167], v[120:123]
	v_mfma_f32_16x16x32_bf16 v[108:111], v[236:239], v[172:175], v[108:111]
	v_mfma_f32_16x16x32_bf16 v[104:107], v[244:247], v[172:175], v[104:107]
	v_mfma_f32_16x16x32_bf16 v[92:95], v[236:239], v[184:187], v[92:95]
	v_mfma_f32_16x16x32_bf16 v[88:91], v[244:247], v[184:187], v[88:91]
	v_mfma_f32_16x16x32_bf16 v[76:79], v[236:239], v[192:195], v[76:79]
	v_mfma_f32_16x16x32_bf16 v[72:75], v[244:247], v[192:195], v[72:75]
	s_setprio 0
	s_mov_b32 m0, s72
	s_barrier
	ds_read_b128 v[160:163], v230 offset:16384
	ds_read_b128 v[164:167], v230 offset:17408
	ds_read_b128 v[168:171], v230 offset:18432
	ds_read_b128 v[172:175], v230 offset:19456
	ds_read_b128 v[180:183], v230 offset:20480
	ds_read_b128 v[184:187], v230 offset:21504
	ds_read_b128 v[188:191], v230 offset:22528
	global_load_lds_dwordx4 v0, s[70:71]
	s_mov_b32 m0, s73
	ds_read_b128 v[192:195], v230 offset:23552
	global_load_lds_dwordx4 v2, s[70:71]
	s_barrier
	s_waitcnt lgkmcnt(0)
	s_setprio 1
	s_waitcnt lgkmcnt(0)
	v_mfma_f32_16x16x32_bf16 v[68:71], v[144:147], v[160:163], v[68:71]
	v_mfma_f32_16x16x32_bf16 v[64:67], v[152:155], v[160:163], v[64:67]
	v_mfma_f32_16x16x32_bf16 v[52:55], v[144:147], v[168:171], v[52:55]
	v_mfma_f32_16x16x32_bf16 v[48:51], v[152:155], v[168:171], v[48:51]
	v_mfma_f32_16x16x32_bf16 v[36:39], v[144:147], v[180:183], v[36:39]
	v_mfma_f32_16x16x32_bf16 v[32:35], v[152:155], v[180:183], v[32:35]
	v_mfma_f32_16x16x32_bf16 v[20:23], v[144:147], v[188:191], v[20:23]
	v_mfma_f32_16x16x32_bf16 v[16:19], v[152:155], v[188:191], v[16:19]
	v_mfma_f32_16x16x32_bf16 v[68:71], v[148:151], v[164:167], v[68:71]
	v_mfma_f32_16x16x32_bf16 v[64:67], v[156:159], v[164:167], v[64:67]
	v_mfma_f32_16x16x32_bf16 v[52:55], v[148:151], v[172:175], v[52:55]
	v_mfma_f32_16x16x32_bf16 v[48:51], v[156:159], v[172:175], v[48:51]
	v_mfma_f32_16x16x32_bf16 v[36:39], v[148:151], v[184:187], v[36:39]
	v_mfma_f32_16x16x32_bf16 v[32:35], v[156:159], v[184:187], v[32:35]
	v_mfma_f32_16x16x32_bf16 v[20:23], v[148:151], v[192:195], v[20:23]
	v_mfma_f32_16x16x32_bf16 v[16:19], v[156:159], v[192:195], v[16:19]
	s_setprio 0
	s_barrier
	s_add_u32 s64, s68, 0x40000
	s_addc_u32 s65, s69, 0
	s_add_i32 m0, s21, 0x14000
	s_nop 0
	global_load_lds_dwordx4 v0, s[64:65]
	s_add_i32 m0, s21, 0x16000
	s_nop 0
	global_load_lds_dwordx4 v2, s[64:65]
	s_waitcnt vmcnt(6)
	s_barrier
; #define G_STAGE(bufoff, gbase) do { _Pragma("unroll") for (int _i = 0; _i < 2; ++_i) \
;         __builtin_amdgcn_global_load_lds((const unsigned*)((const char*)(gbase) + voff[_i]), (LAS unsigned*)(lds + (bufoff) + ldsw + _i * 8192), 16, 0, 0); } while (0)
; #define G_LDA(dst, b, h) do { _Pragma("unroll") for (int m = 0; m < 4; ++m) _Pragma("unroll") for (int k = 0; k < 2; ++k) dst[m][k] = *(const LAS bf16x8*)(lds + G_SA(b, h) + aoff + m * 2048 + k * 1024); } while (0)
; #define G_LDB(dst, b, h) do { _Pragma("unroll") for (int n = 0; n < 2; ++n) _Pragma("unroll") for (int k = 0; k < 2; ++k) dst[n][k] = *(const LAS bf16x8*)(lds + G_SB(b, h) + boff + n * 2048 + k * 1024); } while (0)
; #define G_MMA(ai, bj, At, Bt) do { __builtin_amdgcn_s_setprio(1); _Pragma("unroll") for (int m = 0; m < 4; ++m) _Pragma("unroll") for (int n = 0; n < 2; ++n) _Pragma("unroll") for (int k = 0; k < 2; ++k) \
;         acc[ai][bj][m][n] = MFMA16(Bt[n][k], At[m][k], acc[ai][bj][m][n]); __builtin_amdgcn_s_setprio(0); } while (0)
; #define G_WAIT_V(n) asm volatile("s_waitcnt vmcnt(" #n ")" ::: "memory")
; #define G_WAIT_L(n) asm volatile("s_waitcnt lgkmcnt(" #n ")" ::: "memory")
; #define G_BAR __builtin_amdgcn_s_barrier()
; #define G_SCHED __builtin_amdgcn_sched_barrier(0)
; template <class Epi>
; __device__ __forceinline__ void gemm_phase(LAS unsigned char* lds, const bf16_t* Ag, const bf16_t* Btg, const int K, const int nM, const int nN, const Epi& E) {
;     ...
;             G_WAIT_V(6); G_BAR; G_MMA(1, 1, At, B1); G_BAR;
;             G_LDB(B0, 1, 0); G_SCHED; G_LDA(At, 1, 0); G_STAGE(G_SA(0, 1), a2 + hstep);
;             G_WAIT_L(8); G_BAR; G_WAIT_L(0); G_MMA(0, 0, At, B0); G_BAR; G_SCHED;
;             G_LDB(B1, 1, 1); G_STAGE(G_SB(1, 0), b3);
	s_setprio 1
	v_mfma_f32_16x16x32_bf16 v[60:63], v[232:235], v[160:163], v[60:63]
	v_mfma_f32_16x16x32_bf16 v[56:59], v[240:243], v[160:163], v[56:59]
	v_mfma_f32_16x16x32_bf16 v[44:47], v[232:235], v[168:171], v[44:47]
	v_mfma_f32_16x16x32_bf16 v[40:43], v[240:243], v[168:171], v[40:43]
	v_mfma_f32_16x16x32_bf16 v[28:31], v[232:235], v[180:183], v[28:31]
	v_mfma_f32_16x16x32_bf16 v[24:27], v[240:243], v[180:183], v[24:27]
	v_mfma_f32_16x16x32_bf16 v[12:15], v[232:235], v[188:191], v[12:15]
	v_mfma_f32_16x16x32_bf16 v[8:11], v[240:243], v[188:191], v[8:11]
	v_mfma_f32_16x16x32_bf16 v[60:63], v[236:239], v[164:167], v[60:63]
	v_mfma_f32_16x16x32_bf16 v[56:59], v[244:247], v[164:167], v[56:59]
	v_mfma_f32_16x16x32_bf16 v[44:47], v[236:239], v[172:175], v[44:47]
	v_mfma_f32_16x16x32_bf16 v[40:43], v[244:247], v[172:175], v[40:43]
	v_mfma_f32_16x16x32_bf16 v[28:31], v[236:239], v[184:187], v[28:31]
	v_mfma_f32_16x16x32_bf16 v[24:27], v[244:247], v[184:187], v[24:27]
	v_mfma_f32_16x16x32_bf16 v[12:15], v[236:239], v[192:195], v[12:15]
	v_mfma_f32_16x16x32_bf16 v[8:11], v[244:247], v[192:195], v[8:11]
	s_setprio 0
	s_barrier
	ds_read_b128 v[144:147], v217 offset:32768
	ds_read_b128 v[148:151], v217 offset:33792
	ds_read_b128 v[152:155], v217 offset:34816
	ds_read_b128 v[156:159], v217 offset:35840
	s_add_u32 s64, s70, 0x40000
	s_addc_u32 s65, s71, 0
	s_mov_b32 m0, s74
	ds_read_b128 v[160:163], v230 offset:32768
	ds_read_b128 v[164:167], v230 offset:33792
	ds_read_b128 v[168:171], v230 offset:34816
	ds_read_b128 v[172:175], v230 offset:35840
	ds_read_b128 v[180:183], v230 offset:36864
	ds_read_b128 v[184:187], v230 offset:37888
	ds_read_b128 v[188:191], v230 offset:38912
	global_load_lds_dwordx4 v0, s[64:65]
	s_mov_b32 m0, s75
	ds_read_b128 v[192:195], v230 offset:39936
	global_load_lds_dwordx4 v2, s[64:65]
	s_waitcnt lgkmcnt(8)
	s_barrier
	s_waitcnt lgkmcnt(0)
	s_setprio 1
	s_waitcnt lgkmcnt(0)
	v_mfma_f32_16x16x32_bf16 v[132:135], v[144:147], v[160:163], v[132:135]
	v_mfma_f32_16x16x32_bf16 v[128:131], v[152:155], v[160:163], v[128:131]
	v_mfma_f32_16x16x32_bf16 v[116:119], v[144:147], v[168:171], v[116:119]
	v_mfma_f32_16x16x32_bf16 v[112:115], v[152:155], v[168:171], v[112:115]
	v_mfma_f32_16x16x32_bf16 v[100:103], v[144:147], v[180:183], v[100:103]
	v_mfma_f32_16x16x32_bf16 v[96:99], v[152:155], v[180:183], v[96:99]
	v_mfma_f32_16x16x32_bf16 v[84:87], v[144:147], v[188:191], v[84:87]
	v_mfma_f32_16x16x32_bf16 v[80:83], v[152:155], v[188:191], v[80:83]
	v_mfma_f32_16x16x32_bf16 v[132:135], v[148:151], v[164:167], v[132:135]
	v_mfma_f32_16x16x32_bf16 v[128:131], v[156:159], v[164:167], v[128:131]
	v_mfma_f32_16x16x32_bf16 v[116:119], v[148:151], v[172:175], v[116:119]
	v_mfma_f32_16x16x32_bf16 v[112:115], v[156:159], v[172:175], v[112:115]
	v_mfma_f32_16x16x32_bf16 v[100:103], v[148:151], v[184:187], v[100:103]
	v_mfma_f32_16x16x32_bf16 v[96:99], v[156:159], v[184:187], v[96:99]
	v_mfma_f32_16x16x32_bf16 v[84:87], v[148:151], v[192:195], v[84:87]
	v_mfma_f32_16x16x32_bf16 v[80:83], v[156:159], v[192:195], v[80:83]
	s_setprio 0
	s_barrier
	s_add_i32 s26, 0, 0x1c000
	s_add_i32 m0, s21, 0x18000
	ds_read_b128 v[232:235], v217 offset:49152
	ds_read_b128 v[236:239], v217 offset:50176
	ds_read_b128 v[240:243], v217 offset:51200
	ds_read_b128 v[244:247], v217 offset:52224
	s_add_u32 s98, s68, 0x80
	s_addc_u32 s99, s69, 0
	global_load_lds_dwordx4 v0, s[98:99]
	s_add_i32 m0, s21, 0x1a000
	s_nop 0
	global_load_lds_dwordx4 v2, s[98:99]
	s_barrier
; #define G_STAGE(bufoff, gbase) do { _Pragma("unroll") for (int _i = 0; _i < 2; ++_i) \
;         __builtin_amdgcn_global_load_lds((const unsigned*)((const char*)(gbase) + voff[_i]), (LAS unsigned*)(lds + (bufoff) + ldsw + _i * 8192), 16, 0, 0); } while (0)
; #define G_LDA(dst, b, h) do { _Pragma("unroll") for (int m = 0; m < 4; ++m) _Pragma("unroll") for (int k = 0; k < 2; ++k) dst[m][k] = *(const LAS bf16x8*)(lds + G_SA(b, h) + aoff + m * 2048 + k * 1024); } while (0)
; #define G_MMA(ai, bj, At, Bt) do { __builtin_amdgcn_s_setprio(1); _Pragma("unroll") for (int m = 0; m < 4; ++m) _Pragma("unroll") for (int n = 0; n < 2; ++n) _Pragma("unroll") for (int k = 0; k < 2; ++k) \
;         acc[ai][bj][m][n] = MFMA16(Bt[n][k], At[m][k], acc[ai][bj][m][n]); __builtin_amdgcn_s_setprio(0); } while (0)
; #define G_WAIT_V(n) asm volatile("s_waitcnt vmcnt(" #n ")" ::: "memory")
; #define G_WAIT_L(n) asm volatile("s_waitcnt lgkmcnt(" #n ")" ::: "memory")
; #define G_BAR __builtin_amdgcn_s_barrier()
; #define G_SCHED __builtin_amdgcn_sched_barrier(0)
; template <class Epi>
; __device__ __forceinline__ void gemm_phase(LAS unsigned char* lds, const bf16_t* Ag, const bf16_t* Btg, const int K, const int nM, const int nN, const Epi& E) {
;     ...
;         for (int t = 0; t < nt; t += 2) {
;     ...
;             G_BAR; G_WAIT_L(0); G_MMA(0, 1, At, B1); G_BAR;
;             G_LDA(At, 1, 1); G_STAGE(G_SA(1, 0), a3);
;             G_BAR; G_WAIT_L(0); G_MMA(1, 0, At, B0); G_BAR; G_SCHED;
;             G_STAGE(G_SB(1, 1), b3 + hstep);
;             G_WAIT_V(6); G_BAR; G_MMA(1, 1, At, B1); G_BAR;
	s_waitcnt lgkmcnt(0)
	s_setprio 1
	s_waitcnt lgkmcnt(0)
	v_mfma_f32_16x16x32_bf16 v[124:127], v[232:235], v[160:163], v[124:127]
	v_mfma_f32_16x16x32_bf16 v[120:123], v[240:243], v[160:163], v[120:123]
	v_mfma_f32_16x16x32_bf16 v[108:111], v[232:235], v[168:171], v[108:111]
	v_mfma_f32_16x16x32_bf16 v[104:107], v[240:243], v[168:171], v[104:107]
	v_mfma_f32_16x16x32_bf16 v[92:95], v[232:235], v[180:183], v[92:95]
	v_mfma_f32_16x16x32_bf16 v[88:91], v[240:243], v[180:183], v[88:91]
	v_mfma_f32_16x16x32_bf16 v[76:79], v[232:235], v[188:191], v[76:79]
	v_mfma_f32_16x16x32_bf16 v[72:75], v[240:243], v[188:191], v[72:75]
	v_mfma_f32_16x16x32_bf16 v[124:127], v[236:239], v[164:167], v[124:127]
	v_mfma_f32_16x16x32_bf16 v[120:123], v[244:247], v[164:167], v[120:123]
	v_mfma_f32_16x16x32_bf16 v[108:111], v[236:239], v[172:175], v[108:111]
	v_mfma_f32_16x16x32_bf16 v[104:107], v[244:247], v[172:175], v[104:107]
	v_mfma_f32_16x16x32_bf16 v[92:95], v[236:239], v[184:187], v[92:95]
	v_mfma_f32_16x16x32_bf16 v[88:91], v[244:247], v[184:187], v[88:91]
	v_mfma_f32_16x16x32_bf16 v[76:79], v[236:239], v[192:195], v[76:79]
	v_mfma_f32_16x16x32_bf16 v[72:75], v[244:247], v[192:195], v[72:75]
	s_setprio 0
	s_mov_b32 m0, s76
	s_barrier
	ds_read_b128 v[160:163], v230 offset:49152
	ds_read_b128 v[164:167], v230 offset:50176
	ds_read_b128 v[168:171], v230 offset:51200
	ds_read_b128 v[172:175], v230 offset:52224
	ds_read_b128 v[180:183], v230 offset:53248
	ds_read_b128 v[184:187], v230 offset:54272
	ds_read_b128 v[188:191], v230 offset:55296
	ds_read_b128 v[192:195], v230 offset:56320
	s_add_u32 s98, s70, 0x80
	s_addc_u32 s99, s71, 0
	global_load_lds_dwordx4 v0, s[98:99]
	s_mov_b32 m0, s77
	s_nop 0
	global_load_lds_dwordx4 v2, s[98:99]
	s_barrier
	s_waitcnt lgkmcnt(0)
	s_setprio 1
	s_waitcnt lgkmcnt(0)
	v_mfma_f32_16x16x32_bf16 v[68:71], v[144:147], v[160:163], v[68:71]
	v_mfma_f32_16x16x32_bf16 v[64:67], v[152:155], v[160:163], v[64:67]
	v_mfma_f32_16x16x32_bf16 v[52:55], v[144:147], v[168:171], v[52:55]
	v_mfma_f32_16x16x32_bf16 v[48:51], v[152:155], v[168:171], v[48:51]
	v_mfma_f32_16x16x32_bf16 v[36:39], v[144:147], v[180:183], v[36:39]
	v_mfma_f32_16x16x32_bf16 v[32:35], v[152:155], v[180:183], v[32:35]
	v_mfma_f32_16x16x32_bf16 v[20:23], v[144:147], v[188:191], v[20:23]
	v_mfma_f32_16x16x32_bf16 v[16:19], v[152:155], v[188:191], v[16:19]
	v_mfma_f32_16x16x32_bf16 v[68:71], v[148:151], v[164:167], v[68:71]
	v_mfma_f32_16x16x32_bf16 v[64:67], v[156:159], v[164:167], v[64:67]
	v_mfma_f32_16x16x32_bf16 v[52:55], v[148:151], v[172:175], v[52:55]
	v_mfma_f32_16x16x32_bf16 v[48:51], v[156:159], v[172:175], v[48:51]
	v_mfma_f32_16x16x32_bf16 v[36:39], v[148:151], v[184:187], v[36:39]
	v_mfma_f32_16x16x32_bf16 v[32:35], v[156:159], v[184:187], v[32:35]
	v_mfma_f32_16x16x32_bf16 v[20:23], v[148:151], v[192:195], v[20:23]
	v_mfma_f32_16x16x32_bf16 v[16:19], v[156:159], v[192:195], v[16:19]
	s_setprio 0
	s_barrier
	s_add_u32 s64, s68, 0x40080
	s_addc_u32 s65, s69, 0
	s_add_i32 s12, s26, s21
	s_add_i32 m0, s21, 0x1c000
	s_nop 0
	global_load_lds_dwordx4 v0, s[64:65]
	s_add_i32 m0, s21, 0x1e000
	s_nop 0
	global_load_lds_dwordx4 v2, s[64:65]
	s_waitcnt vmcnt(6)
	s_barrier
	s_setprio 1
	v_mfma_f32_16x16x32_bf16 v[60:63], v[232:235], v[160:163], v[60:63]
	v_mfma_f32_16x16x32_bf16 v[56:59], v[240:243], v[160:163], v[56:59]
	v_mfma_f32_16x16x32_bf16 v[44:47], v[232:235], v[168:171], v[44:47]
	v_mfma_f32_16x16x32_bf16 v[40:43], v[240:243], v[168:171], v[40:43]
	v_mfma_f32_16x16x32_bf16 v[28:31], v[232:235], v[180:183], v[28:31]
	v_mfma_f32_16x16x32_bf16 v[24:27], v[240:243], v[180:183], v[24:27]
	v_mfma_f32_16x16x32_bf16 v[12:15], v[232:235], v[188:191], v[12:15]
	v_mfma_f32_16x16x32_bf16 v[8:11], v[240:243], v[188:191], v[8:11]
	v_mfma_f32_16x16x32_bf16 v[60:63], v[236:239], v[164:167], v[60:63]
	v_mfma_f32_16x16x32_bf16 v[56:59], v[244:247], v[164:167], v[56:59]
	v_mfma_f32_16x16x32_bf16 v[44:47], v[236:239], v[172:175], v[44:47]
	v_mfma_f32_16x16x32_bf16 v[40:43], v[244:247], v[172:175], v[40:43]
	v_mfma_f32_16x16x32_bf16 v[28:31], v[236:239], v[184:187], v[28:31]
	v_mfma_f32_16x16x32_bf16 v[24:27], v[244:247], v[184:187], v[24:27]
	v_mfma_f32_16x16x32_bf16 v[12:15], v[236:239], v[192:195], v[12:15]
	v_mfma_f32_16x16x32_bf16 v[8:11], v[244:247], v[192:195], v[8:11]
	s_setprio 0
	s_add_i32 s42, s42, 2
	s_add_u32 s57, s57, 0x100
	s_addc_u32 s61, s61, 0
	s_cmp_gt_u32 s42, 13
	s_mov_b64 s[64:65], s[66:67]
	s_barrier
	s_cbranch_scc1 .LBB0_157

; __device__ __forceinline__ int prow0(int pm) { return (pm >> 4) * LP + PADR + (pm & 15) * 256; }
; template <class Epi>
; __device__ __forceinline__ void gemm_phase(LAS unsigned char* lds, const bf16_t* Ag, const bf16_t* Btg, const int K, const int nM, const int nN, const Epi& E) {
;     ...
;         const int un = u + G; const bool has_next = un < nunits; const int pmn = has_next ? un % nM : pm, pnn = has_next ? un / nM : pn;
;         const char* nA = has_next ? (const char*)Ag + (size_t)prow0(pmn) * rstep : cA; const char* nB = has_next ? (const char*)Btg + (size_t)pnn * tstep : cB;
.LBB0_738:
	v_add_u32_e32 v217, 0x10000, v165
	s_add_i32 s73, s73, s13
	s_cmpk_gt_i32 s73, 0xff
	s_cselect_b64 s[54:55], -1, 0
	s_cmpk_lt_i32 s73, 0x100
	s_cselect_b64 s[24:25], -1, 0
	s_ashr_i32 s12, s73, 31
	s_lshr_b32 s12, s12, 26
	s_add_i32 s12, s73, s12
	s_and_b32 s14, s12, 0xffffffc0
	s_sub_i32 s75, s73, s14
	s_lshl_b32 s14, s75, 8
	s_and_b32 s26, s14, 0xf00
	s_mov_b64 s[14:15], -1
	s_and_b64 vcc, exec, s[24:25]
	s_cbranch_vccz .LBB0_740
	s_lshr_b32 s14, s75, 4
	s_mulk_i32 s14, 0x1040
	s_add_i32 s14, s26, s14
	s_add_i32 s52, s14, 48
	s_ashr_i32 s53, s52, 31
	s_lshl_b64 s[14:15], s[52:53], 13
	s_add_u32 s46, s86, s14
	s_addc_u32 s47, s87, s15
	s_mov_b64 s[14:15], 0

;     __device__ __forceinline__ void prep(int pm, int par, LAS unsigned char* lds) const { if (fold) prep_rowstats(stat, pm, par, lds); }
;     __device__ __forceinline__ void prep(int pm, int par, LAS unsigned char* lds) const { if (!ident) prep_rowstats(stat, pm, par, lds); }
;     __device__ __forceinline__ void prep(int pm, int par, LAS unsigned char* lds) const { prep_rowstats(stat, pm, par, lds); }
; #define G_STAGE(bufoff, gbase) do { _Pragma("unroll") for (int _i = 0; _i < 2; ++_i) \
;         __builtin_amdgcn_global_load_lds((const unsigned*)((const char*)(gbase) + voff[_i]), (LAS unsigned*)(lds + (bufoff) + ldsw + _i * 8192), 16, 0, 0); } while (0)
; #define G_LDA(dst, b, h) do { _Pragma("unroll") for (int m = 0; m < 4; ++m) _Pragma("unroll") for (int k = 0; k < 2; ++k) dst[m][k] = *(const LAS bf16x8*)(lds + G_SA(b, h) + aoff + m * 2048 + k * 1024); } while (0)
; #define G_LDB(dst, b, h) do { _Pragma("unroll") for (int n = 0; n < 2; ++n) _Pragma("unroll") for (int k = 0; k < 2; ++k) dst[n][k] = *(const LAS bf16x8*)(lds + G_SB(b, h) + boff + n * 2048 + k * 1024); } while (0)
; #define G_WAIT_L(n) asm volatile("s_waitcnt lgkmcnt(" #n ")" ::: "memory")
; #define G_BAR __builtin_amdgcn_s_barrier()
; #define G_SCHED __builtin_amdgcn_sched_barrier(0)
; template <class Epi>
; __device__ __forceinline__ void gemm_phase(LAS unsigned char* lds, const bf16_t* Ag, const bf16_t* Btg, const int K, const int nM, const int nN, const Epi& E) {
;     ...
;         for (int t = 0; t < nt; t += 2) {
;             const bool last = (t == nt - 2);
;             const char* a1 = cA + (size_t)(t + 1) * kstep;
;             const char* a2 = last ? nA : cA + (size_t)(t + 2) * kstep; const char* b2 = last ? nB : cB + (size_t)(t + 2) * kstep;
;             const char* a3 = a2 + kstep; const char* b3 = b2 + kstep;
;             if (last && has_next && pmn != pm) E.prep(pmn, par ^ 1, lds);
;             G_LDB(B0, 0, 0); G_SCHED; G_LDA(At, 0, 0); G_STAGE(G_SA(1, 1), a1 + hstep);
;             G_WAIT_L(8); G_BAR; G_WAIT_L(0); G_MMA(0, 0, At, B0); G_BAR; G_SCHED;
;             G_LDB(B1, 0, 1); G_STAGE(G_SB(0, 0), b2);
;             G_BAR; G_WAIT_L(0); G_MMA(0, 1, At, B1); G_BAR;
;             G_LDA(At, 0, 1); G_STAGE(G_SA(0, 0), a2);
;             G_BAR; G_WAIT_L(0); G_MMA(1, 0, At, B0); G_BAR; G_SCHED;
;             G_STAGE(G_SB(0, 1), b2 + hstep);
.LBB0_744:
	s_add_u32 s58, s56, 0x100
	s_addc_u32 s59, s57, 0
	s_and_b64 s[60:61], s[60:61], exec
	s_cselect_b32 s63, s59, s47
	s_cselect_b32 s62, s58, s46
	s_cselect_b32 s61, s78, s15
	s_cselect_b32 s60, s77, s49
	ds_read_b128 v[140:143], v217
	ds_read_b128 v[144:147], v217 offset:1024
	ds_read_b128 v[148:151], v217 offset:2048
	ds_read_b128 v[152:155], v217 offset:3072
	s_add_i32 m0, s66, 0xc000
	ds_read_b128 v[156:159], v174
	ds_read_b128 v[160:163], v174 offset:1024
	ds_read_b128 v[180:183], v174 offset:2048
	ds_read_b128 v[184:187], v174 offset:3072
	ds_read_b128 v[188:191], v174 offset:4096
	ds_read_b128 v[192:195], v174 offset:5120
	ds_read_b128 v[222:225], v174 offset:6144
	global_load_lds_dwordx4 v138, s[56:57]
	s_add_i32 m0, s66, 0xe000
	ds_read_b128 v[226:229], v174 offset:7168
	global_load_lds_dwordx4 v136, s[56:57]
	s_waitcnt lgkmcnt(8)
	s_barrier
	s_waitcnt lgkmcnt(0)
	s_setprio 1
	s_waitcnt lgkmcnt(0)
	v_mfma_f32_16x16x32_bf16 v[132:135], v[140:143], v[156:159], v[132:135]
	v_mfma_f32_16x16x32_bf16 v[128:131], v[148:151], v[156:159], v[128:131]
	v_mfma_f32_16x16x32_bf16 v[116:119], v[140:143], v[180:183], v[116:119]
	v_mfma_f32_16x16x32_bf16 v[112:115], v[148:151], v[180:183], v[112:115]
	v_mfma_f32_16x16x32_bf16 v[100:103], v[140:143], v[188:191], v[100:103]
	v_mfma_f32_16x16x32_bf16 v[96:99], v[148:151], v[188:191], v[96:99]
	v_mfma_f32_16x16x32_bf16 v[84:87], v[140:143], v[222:225], v[84:87]
	v_mfma_f32_16x16x32_bf16 v[80:83], v[148:151], v[222:225], v[80:83]
	v_mfma_f32_16x16x32_bf16 v[132:135], v[144:147], v[160:163], v[132:135]
	v_mfma_f32_16x16x32_bf16 v[128:131], v[152:155], v[160:163], v[128:131]
	v_mfma_f32_16x16x32_bf16 v[116:119], v[144:147], v[184:187], v[116:119]
	v_mfma_f32_16x16x32_bf16 v[112:115], v[152:155], v[184:187], v[112:115]
	v_mfma_f32_16x16x32_bf16 v[100:103], v[144:147], v[192:195], v[100:103]
	v_mfma_f32_16x16x32_bf16 v[96:99], v[152:155], v[192:195], v[96:99]
	v_mfma_f32_16x16x32_bf16 v[84:87], v[144:147], v[226:229], v[84:87]
	v_mfma_f32_16x16x32_bf16 v[80:83], v[152:155], v[226:229], v[80:83]
	s_setprio 0
	s_barrier
	s_add_i32 m0, s65, 0x10000
	ds_read_b128 v[230:233], v217 offset:16384
	ds_read_b128 v[234:237], v217 offset:17408
	ds_read_b128 v[238:241], v217 offset:18432
	global_load_lds_dwordx4 v0, s[60:61]
	s_add_i32 m0, s65, 0x12000
	ds_read_b128 v[242:245], v217 offset:19456
	global_load_lds_dwordx4 v2, s[60:61]
	s_barrier
	s_waitcnt lgkmcnt(0)
	s_setprio 1
	s_waitcnt lgkmcnt(0)
	v_mfma_f32_16x16x32_bf16 v[124:127], v[230:233], v[156:159], v[124:127]
	v_mfma_f32_16x16x32_bf16 v[120:123], v[238:241], v[156:159], v[120:123]
	v_mfma_f32_16x16x32_bf16 v[108:111], v[230:233], v[180:183], v[108:111]
	v_mfma_f32_16x16x32_bf16 v[104:107], v[238:241], v[180:183], v[104:107]
	v_mfma_f32_16x16x32_bf16 v[92:95], v[230:233], v[188:191], v[92:95]
	v_mfma_f32_16x16x32_bf16 v[88:91], v[238:241], v[188:191], v[88:91]
	v_mfma_f32_16x16x32_bf16 v[76:79], v[230:233], v[222:225], v[76:79]
	v_mfma_f32_16x16x32_bf16 v[72:75], v[238:241], v[222:225], v[72:75]
	v_mfma_f32_16x16x32_bf16 v[124:127], v[234:237], v[160:163], v[124:127]
	v_mfma_f32_16x16x32_bf16 v[120:123], v[242:245], v[160:163], v[120:123]
	v_mfma_f32_16x16x32_bf16 v[108:111], v[234:237], v[184:187], v[108:111]
	v_mfma_f32_16x16x32_bf16 v[104:107], v[242:245], v[184:187], v[104:107]
	v_mfma_f32_16x16x32_bf16 v[92:95], v[234:237], v[192:195], v[92:95]
	v_mfma_f32_16x16x32_bf16 v[88:91], v[242:245], v[192:195], v[88:91]
	v_mfma_f32_16x16x32_bf16 v[76:79], v[234:237], v[226:229], v[76:79]
	v_mfma_f32_16x16x32_bf16 v[72:75], v[242:245], v[226:229], v[72:75]
	s_setprio 0
	s_mov_b32 m0, s66
	s_barrier
	ds_read_b128 v[156:159], v174 offset:16384
	ds_read_b128 v[160:163], v174 offset:17408
	ds_read_b128 v[180:183], v174 offset:18432
	ds_read_b128 v[184:187], v174 offset:19456
	ds_read_b128 v[188:191], v174 offset:20480
	ds_read_b128 v[192:195], v174 offset:21504
	ds_read_b128 v[222:225], v174 offset:22528
	global_load_lds_dwordx4 v0, s[62:63]
	s_mov_b32 m0, s67
	ds_read_b128 v[226:229], v174 offset:23552
	global_load_lds_dwordx4 v2, s[62:63]
	s_barrier
	s_waitcnt lgkmcnt(0)
	s_setprio 1
	s_waitcnt lgkmcnt(0)
	v_mfma_f32_16x16x32_bf16 v[68:71], v[140:143], v[156:159], v[68:71]
	v_mfma_f32_16x16x32_bf16 v[64:67], v[148:151], v[156:159], v[64:67]
	v_mfma_f32_16x16x32_bf16 v[52:55], v[140:143], v[180:183], v[52:55]
	v_mfma_f32_16x16x32_bf16 v[48:51], v[148:151], v[180:183], v[48:51]
	v_mfma_f32_16x16x32_bf16 v[36:39], v[140:143], v[188:191], v[36:39]
	v_mfma_f32_16x16x32_bf16 v[32:35], v[148:151], v[188:191], v[32:35]
	v_mfma_f32_16x16x32_bf16 v[20:23], v[140:143], v[222:225], v[20:23]
	v_mfma_f32_16x16x32_bf16 v[16:19], v[148:151], v[222:225], v[16:19]
	v_mfma_f32_16x16x32_bf16 v[68:71], v[144:147], v[160:163], v[68:71]
	v_mfma_f32_16x16x32_bf16 v[64:67], v[152:155], v[160:163], v[64:67]
	v_mfma_f32_16x16x32_bf16 v[52:55], v[144:147], v[184:187], v[52:55]
	v_mfma_f32_16x16x32_bf16 v[48:51], v[152:155], v[184:187], v[48:51]
	v_mfma_f32_16x16x32_bf16 v[36:39], v[144:147], v[192:195], v[36:39]
	v_mfma_f32_16x16x32_bf16 v[32:35], v[152:155], v[192:195], v[32:35]
	v_mfma_f32_16x16x32_bf16 v[20:23], v[144:147], v[226:229], v[20:23]
	v_mfma_f32_16x16x32_bf16 v[16:19], v[152:155], v[226:229], v[16:19]
	s_setprio 0
	s_barrier
	s_add_u32 s56, s60, 0x100000
	s_addc_u32 s57, s61, 0
	s_add_i32 m0, s65, 0x14000
	s_nop 0
	global_load_lds_dwordx4 v0, s[56:57]
	s_add_i32 m0, s65, 0x16000
	s_nop 0
	global_load_lds_dwordx4 v2, s[56:57]
	s_waitcnt vmcnt(6)
	s_barrier
; #define G_STAGE(bufoff, gbase) do { _Pragma("unroll") for (int _i = 0; _i < 2; ++_i) \
;         __builtin_amdgcn_global_load_lds((const unsigned*)((const char*)(gbase) + voff[_i]), (LAS unsigned*)(lds + (bufoff) + ldsw + _i * 8192), 16, 0, 0); } while (0)
; #define G_LDA(dst, b, h) do { _Pragma("unroll") for (int m = 0; m < 4; ++m) _Pragma("unroll") for (int k = 0; k < 2; ++k) dst[m][k] = *(const LAS bf16x8*)(lds + G_SA(b, h) + aoff + m * 2048 + k * 1024); } while (0)
; #define G_LDB(dst, b, h) do { _Pragma("unroll") for (int n = 0; n < 2; ++n) _Pragma("unroll") for (int k = 0; k < 2; ++k) dst[n][k] = *(const LAS bf16x8*)(lds + G_SB(b, h) + boff + n * 2048 + k * 1024); } while (0)
; #define G_MMA(ai, bj, At, Bt) do { __builtin_amdgcn_s_setprio(1); _Pragma("unroll") for (int m = 0; m < 4; ++m) _Pragma("unroll") for (int n = 0; n < 2; ++n) _Pragma("unroll") for (int k = 0; k < 2; ++k) \
;         acc[ai][bj][m][n] = MFMA16(Bt[n][k], At[m][k], acc[ai][bj][m][n]); __builtin_amdgcn_s_setprio(0); } while (0)
; #define G_WAIT_V(n) asm volatile("s_waitcnt vmcnt(" #n ")" ::: "memory")
; #define G_WAIT_L(n) asm volatile("s_waitcnt lgkmcnt(" #n ")" ::: "memory")
; #define G_BAR __builtin_amdgcn_s_barrier()
; #define G_SCHED __builtin_amdgcn_sched_barrier(0)
; template <class Epi>
; __device__ __forceinline__ void gemm_phase(LAS unsigned char* lds, const bf16_t* Ag, const bf16_t* Btg, const int K, const int nM, const int nN, const Epi& E) {
;     ...
;             G_WAIT_V(6); G_BAR; G_MMA(1, 1, At, B1); G_BAR;
;             G_LDB(B0, 1, 0); G_SCHED; G_LDA(At, 1, 0); G_STAGE(G_SA(0, 1), a2 + hstep);
;             G_WAIT_L(8); G_BAR; G_WAIT_L(0); G_MMA(0, 0, At, B0); G_BAR; G_SCHED;
;             G_LDB(B1, 1, 1); G_STAGE(G_SB(1, 0), b3);
	s_setprio 1
	v_mfma_f32_16x16x32_bf16 v[60:63], v[230:233], v[156:159], v[60:63]
	v_mfma_f32_16x16x32_bf16 v[56:59], v[238:241], v[156:159], v[56:59]
	v_mfma_f32_16x16x32_bf16 v[44:47], v[230:233], v[180:183], v[44:47]
	v_mfma_f32_16x16x32_bf16 v[40:43], v[238:241], v[180:183], v[40:43]
	v_mfma_f32_16x16x32_bf16 v[28:31], v[230:233], v[188:191], v[28:31]
	v_mfma_f32_16x16x32_bf16 v[24:27], v[238:241], v[188:191], v[24:27]
	v_mfma_f32_16x16x32_bf16 v[12:15], v[230:233], v[222:225], v[12:15]
	v_mfma_f32_16x16x32_bf16 v[8:11], v[238:241], v[222:225], v[8:11]
	v_mfma_f32_16x16x32_bf16 v[60:63], v[234:237], v[160:163], v[60:63]
	v_mfma_f32_16x16x32_bf16 v[56:59], v[242:245], v[160:163], v[56:59]
	v_mfma_f32_16x16x32_bf16 v[44:47], v[234:237], v[184:187], v[44:47]
	v_mfma_f32_16x16x32_bf16 v[40:43], v[242:245], v[184:187], v[40:43]
	v_mfma_f32_16x16x32_bf16 v[28:31], v[234:237], v[192:195], v[28:31]
	v_mfma_f32_16x16x32_bf16 v[24:27], v[242:245], v[192:195], v[24:27]
	v_mfma_f32_16x16x32_bf16 v[12:15], v[234:237], v[226:229], v[12:15]
	v_mfma_f32_16x16x32_bf16 v[8:11], v[242:245], v[226:229], v[8:11]
	s_setprio 0
	s_barrier
	ds_read_b128 v[140:143], v217 offset:32768
	ds_read_b128 v[144:147], v217 offset:33792
	ds_read_b128 v[148:151], v217 offset:34816
	ds_read_b128 v[152:155], v217 offset:35840
	s_add_u32 s56, s62, 0x100000
	s_addc_u32 s57, s63, 0
	s_mov_b32 m0, s68
	ds_read_b128 v[156:159], v174 offset:32768
	ds_read_b128 v[160:163], v174 offset:33792
	ds_read_b128 v[180:183], v174 offset:34816
	ds_read_b128 v[184:187], v174 offset:35840
	ds_read_b128 v[188:191], v174 offset:36864
	ds_read_b128 v[192:195], v174 offset:37888
	ds_read_b128 v[222:225], v174 offset:38912
	global_load_lds_dwordx4 v0, s[56:57]
	s_mov_b32 m0, s69
	ds_read_b128 v[226:229], v174 offset:39936
	global_load_lds_dwordx4 v2, s[56:57]
	s_waitcnt lgkmcnt(8)
	s_barrier
	s_waitcnt lgkmcnt(0)
	s_setprio 1
	s_waitcnt lgkmcnt(0)
	v_mfma_f32_16x16x32_bf16 v[132:135], v[140:143], v[156:159], v[132:135]
	v_mfma_f32_16x16x32_bf16 v[128:131], v[148:151], v[156:159], v[128:131]
	v_mfma_f32_16x16x32_bf16 v[116:119], v[140:143], v[180:183], v[116:119]
	v_mfma_f32_16x16x32_bf16 v[112:115], v[148:151], v[180:183], v[112:115]
	v_mfma_f32_16x16x32_bf16 v[100:103], v[140:143], v[188:191], v[100:103]
	v_mfma_f32_16x16x32_bf16 v[96:99], v[148:151], v[188:191], v[96:99]
	v_mfma_f32_16x16x32_bf16 v[84:87], v[140:143], v[222:225], v[84:87]
	v_mfma_f32_16x16x32_bf16 v[80:83], v[148:151], v[222:225], v[80:83]
	v_mfma_f32_16x16x32_bf16 v[132:135], v[144:147], v[160:163], v[132:135]
	v_mfma_f32_16x16x32_bf16 v[128:131], v[152:155], v[160:163], v[128:131]
	v_mfma_f32_16x16x32_bf16 v[116:119], v[144:147], v[184:187], v[116:119]
	v_mfma_f32_16x16x32_bf16 v[112:115], v[152:155], v[184:187], v[112:115]
	v_mfma_f32_16x16x32_bf16 v[100:103], v[144:147], v[192:195], v[100:103]
	v_mfma_f32_16x16x32_bf16 v[96:99], v[152:155], v[192:195], v[96:99]
	v_mfma_f32_16x16x32_bf16 v[84:87], v[144:147], v[226:229], v[84:87]
	v_mfma_f32_16x16x32_bf16 v[80:83], v[152:155], v[226:229], v[80:83]
	s_setprio 0
	s_barrier
	s_add_i32 s26, 0, 0x1c000
	s_add_i32 m0, s65, 0x18000
	ds_read_b128 v[230:233], v217 offset:49152
	ds_read_b128 v[234:237], v217 offset:50176
	ds_read_b128 v[238:241], v217 offset:51200
	ds_read_b128 v[242:245], v217 offset:52224
	s_add_u32 s98, s60, 0x80
	s_addc_u32 s99, s61, 0
	global_load_lds_dwordx4 v0, s[98:99]
	s_add_i32 m0, s65, 0x1a000
	s_nop 0
	global_load_lds_dwordx4 v2, s[98:99]
	s_barrier
; #define G_STAGE(bufoff, gbase) do { _Pragma("unroll") for (int _i = 0; _i < 2; ++_i) \
;         __builtin_amdgcn_global_load_lds((const unsigned*)((const char*)(gbase) + voff[_i]), (LAS unsigned*)(lds + (bufoff) + ldsw + _i * 8192), 16, 0, 0); } while (0)
; #define G_LDA(dst, b, h) do { _Pragma("unroll") for (int m = 0; m < 4; ++m) _Pragma("unroll") for (int k = 0; k < 2; ++k) dst[m][k] = *(const LAS bf16x8*)(lds + G_SA(b, h) + aoff + m * 2048 + k * 1024); } while (0)
; #define G_MMA(ai, bj, At, Bt) do { __builtin_amdgcn_s_setprio(1); _Pragma("unroll") for (int m = 0; m < 4; ++m) _Pragma("unroll") for (int n = 0; n < 2; ++n) _Pragma("unroll") for (int k = 0; k < 2; ++k) \
;         acc[ai][bj][m][n] = MFMA16(Bt[n][k], At[m][k], acc[ai][bj][m][n]); __builtin_amdgcn_s_setprio(0); } while (0)
; #define G_WAIT_V(n) asm volatile("s_waitcnt vmcnt(" #n ")" ::: "memory")
; #define G_WAIT_L(n) asm volatile("s_waitcnt lgkmcnt(" #n ")" ::: "memory")
; #define G_BAR __builtin_amdgcn_s_barrier()
; #define G_SCHED __builtin_amdgcn_sched_barrier(0)
; template <class Epi>
; __device__ __forceinline__ void gemm_phase(LAS unsigned char* lds, const bf16_t* Ag, const bf16_t* Btg, const int K, const int nM, const int nN, const Epi& E) {
;     ...
;         for (int t = 0; t < nt; t += 2) {
;     ...
;             G_BAR; G_WAIT_L(0); G_MMA(0, 1, At, B1); G_BAR;
;             G_LDA(At, 1, 1); G_STAGE(G_SA(1, 0), a3);
;             G_BAR; G_WAIT_L(0); G_MMA(1, 0, At, B0); G_BAR; G_SCHED;
;             G_STAGE(G_SB(1, 1), b3 + hstep);
;             G_WAIT_V(6); G_BAR; G_MMA(1, 1, At, B1); G_BAR;
	s_waitcnt lgkmcnt(0)
	s_setprio 1
	s_waitcnt lgkmcnt(0)
	v_mfma_f32_16x16x32_bf16 v[124:127], v[230:233], v[156:159], v[124:127]
	v_mfma_f32_16x16x32_bf16 v[120:123], v[238:241], v[156:159], v[120:123]
	v_mfma_f32_16x16x32_bf16 v[108:111], v[230:233], v[180:183], v[108:111]
	v_mfma_f32_16x16x32_bf16 v[104:107], v[238:241], v[180:183], v[104:107]
	v_mfma_f32_16x16x32_bf16 v[92:95], v[230:233], v[188:191], v[92:95]
	v_mfma_f32_16x16x32_bf16 v[88:91], v[238:241], v[188:191], v[88:91]
	v_mfma_f32_16x16x32_bf16 v[76:79], v[230:233], v[222:225], v[76:79]
	v_mfma_f32_16x16x32_bf16 v[72:75], v[238:241], v[222:225], v[72:75]
	v_mfma_f32_16x16x32_bf16 v[124:127], v[234:237], v[160:163], v[124:127]
	v_mfma_f32_16x16x32_bf16 v[120:123], v[242:245], v[160:163], v[120:123]
	v_mfma_f32_16x16x32_bf16 v[108:111], v[234:237], v[184:187], v[108:111]
	v_mfma_f32_16x16x32_bf16 v[104:107], v[242:245], v[184:187], v[104:107]
	v_mfma_f32_16x16x32_bf16 v[92:95], v[234:237], v[192:195], v[92:95]
	v_mfma_f32_16x16x32_bf16 v[88:91], v[242:245], v[192:195], v[88:91]
	v_mfma_f32_16x16x32_bf16 v[76:79], v[234:237], v[226:229], v[76:79]
	v_mfma_f32_16x16x32_bf16 v[72:75], v[242:245], v[226:229], v[72:75]
	s_setprio 0
	s_mov_b32 m0, s70
	s_barrier
	ds_read_b128 v[156:159], v174 offset:49152
	ds_read_b128 v[160:163], v174 offset:50176
	ds_read_b128 v[180:183], v174 offset:51200
	ds_read_b128 v[184:187], v174 offset:52224
	ds_read_b128 v[188:191], v174 offset:53248
	ds_read_b128 v[192:195], v174 offset:54272
	ds_read_b128 v[222:225], v174 offset:55296
	ds_read_b128 v[226:229], v174 offset:56320
	s_add_u32 s98, s62, 0x80
	s_addc_u32 s99, s63, 0
	global_load_lds_dwordx4 v0, s[98:99]
	s_mov_b32 m0, s71
	s_nop 0
	global_load_lds_dwordx4 v2, s[98:99]
	s_barrier
	s_waitcnt lgkmcnt(0)
	s_setprio 1
	s_waitcnt lgkmcnt(0)
	v_mfma_f32_16x16x32_bf16 v[68:71], v[140:143], v[156:159], v[68:71]
	v_mfma_f32_16x16x32_bf16 v[64:67], v[148:151], v[156:159], v[64:67]
	v_mfma_f32_16x16x32_bf16 v[52:55], v[140:143], v[180:183], v[52:55]
	v_mfma_f32_16x16x32_bf16 v[48:51], v[148:151], v[180:183], v[48:51]
	v_mfma_f32_16x16x32_bf16 v[36:39], v[140:143], v[188:191], v[36:39]
	v_mfma_f32_16x16x32_bf16 v[32:35], v[148:151], v[188:191], v[32:35]
	v_mfma_f32_16x16x32_bf16 v[20:23], v[140:143], v[222:225], v[20:23]
	v_mfma_f32_16x16x32_bf16 v[16:19], v[148:151], v[222:225], v[16:19]
	v_mfma_f32_16x16x32_bf16 v[68:71], v[144:147], v[160:163], v[68:71]
	v_mfma_f32_16x16x32_bf16 v[64:67], v[152:155], v[160:163], v[64:67]
	v_mfma_f32_16x16x32_bf16 v[52:55], v[144:147], v[184:187], v[52:55]
	v_mfma_f32_16x16x32_bf16 v[48:51], v[152:155], v[184:187], v[48:51]
	v_mfma_f32_16x16x32_bf16 v[36:39], v[144:147], v[192:195], v[36:39]
	v_mfma_f32_16x16x32_bf16 v[32:35], v[152:155], v[192:195], v[32:35]
	v_mfma_f32_16x16x32_bf16 v[20:23], v[144:147], v[226:229], v[20:23]
	v_mfma_f32_16x16x32_bf16 v[16:19], v[152:155], v[226:229], v[16:19]
	s_setprio 0
	s_barrier
	s_add_u32 s56, s60, 0x100080
	s_addc_u32 s57, s61, 0
	s_add_i32 s12, s26, s65
	s_add_i32 m0, s65, 0x1c000
	s_nop 0
	global_load_lds_dwordx4 v0, s[56:57]
	s_add_i32 m0, s65, 0x1e000
	s_nop 0
	global_load_lds_dwordx4 v2, s[56:57]
	s_waitcnt vmcnt(6)
	s_barrier
	s_setprio 1
	v_mfma_f32_16x16x32_bf16 v[60:63], v[230:233], v[156:159], v[60:63]
	v_mfma_f32_16x16x32_bf16 v[56:59], v[238:241], v[156:159], v[56:59]
	v_mfma_f32_16x16x32_bf16 v[44:47], v[230:233], v[180:183], v[44:47]
	v_mfma_f32_16x16x32_bf16 v[40:43], v[238:241], v[180:183], v[40:43]
	v_mfma_f32_16x16x32_bf16 v[28:31], v[230:233], v[188:191], v[28:31]
	v_mfma_f32_16x16x32_bf16 v[24:27], v[238:241], v[188:191], v[24:27]
	v_mfma_f32_16x16x32_bf16 v[12:15], v[230:233], v[222:225], v[12:15]
	v_mfma_f32_16x16x32_bf16 v[8:11], v[238:241], v[222:225], v[8:11]
	v_mfma_f32_16x16x32_bf16 v[60:63], v[234:237], v[160:163], v[60:63]
	v_mfma_f32_16x16x32_bf16 v[56:59], v[242:245], v[160:163], v[56:59]
	v_mfma_f32_16x16x32_bf16 v[44:47], v[234:237], v[184:187], v[44:47]
	v_mfma_f32_16x16x32_bf16 v[40:43], v[242:245], v[184:187], v[40:43]
	v_mfma_f32_16x16x32_bf16 v[28:31], v[234:237], v[192:195], v[28:31]
	v_mfma_f32_16x16x32_bf16 v[24:27], v[242:245], v[192:195], v[24:27]
	v_mfma_f32_16x16x32_bf16 v[12:15], v[234:237], v[226:229], v[12:15]
	v_mfma_f32_16x16x32_bf16 v[8:11], v[242:245], v[226:229], v[8:11]
	s_setprio 0
	s_add_i32 s79, s79, 2
	s_add_u32 s77, s77, 0x100
	s_addc_u32 s78, s78, 0
	s_cmp_gt_u32 s79, 61
	s_mov_b64 s[56:57], s[58:59]
	s_barrier
	s_cbranch_scc1 .LBB0_748

; __device__ __forceinline__ int prow0(int pm) { return (pm >> 4) * LP + PADR + (pm & 15) * 256; }
; template <class Epi>
; __device__ __forceinline__ void gemm_phase(LAS unsigned char* lds, const bf16_t* Ag, const bf16_t* Btg, const int K, const int nM, const int nN, const Epi& E) {
;     ...
;         const int un = u + G; const bool has_next = un < nunits; const int pmn = has_next ? un % nM : pm, pnn = has_next ? un / nM : pn;
;         const char* nA = has_next ? (const char*)Ag + (size_t)prow0(pmn) * rstep : cA; const char* nB = has_next ? (const char*)Btg + (size_t)pnn * tstep : cB;
.LBB0_842:
	v_add_u32_e32 v217, 0x10000, v179
	s_add_i32 s66, s66, s57
	s_cmpk_gt_i32 s66, 0x2ff
	s_cselect_b64 s[48:49], -1, 0
	s_cmpk_lt_i32 s66, 0x300
	s_cselect_b64 s[22:23], -1, 0
	s_ashr_i32 s14, s66, 31
	s_lshr_b32 s14, s14, 26
	s_add_i32 s26, s66, s14
	s_and_b32 s14, s26, 0xffffffc0
	s_sub_i32 s67, s66, s14
	s_lshl_b32 s14, s67, 8
	s_and_b32 s44, s14, 0xf00
	s_mov_b64 s[14:15], -1
	s_and_b64 vcc, exec, s[22:23]
	s_cbranch_vccz .LBB0_844
	s_lshr_b32 s14, s67, 4
	s_mulk_i32 s14, 0x1040
	s_add_i32 s14, s44, s14
	s_add_i32 s46, s14, 48
	s_ashr_i32 s47, s46, 31
	s_lshl_b64 s[14:15], s[46:47], 11
	s_add_u32 s24, s36, s14
	s_addc_u32 s25, s37, s15
	s_mov_b64 s[14:15], 0

;     __device__ __forceinline__ void prep(int pm, int par, LAS unsigned char* lds) const { if (fold) prep_rowstats(stat, pm, par, lds); }
;     __device__ __forceinline__ void prep(int pm, int par, LAS unsigned char* lds) const { if (!ident) prep_rowstats(stat, pm, par, lds); }
;     __device__ __forceinline__ void prep(int pm, int par, LAS unsigned char* lds) const { prep_rowstats(stat, pm, par, lds); }
; #define G_STAGE(bufoff, gbase) do { _Pragma("unroll") for (int _i = 0; _i < 2; ++_i) \
;         __builtin_amdgcn_global_load_lds((const unsigned*)((const char*)(gbase) + voff[_i]), (LAS unsigned*)(lds + (bufoff) + ldsw + _i * 8192), 16, 0, 0); } while (0)
; #define G_LDA(dst, b, h) do { _Pragma("unroll") for (int m = 0; m < 4; ++m) _Pragma("unroll") for (int k = 0; k < 2; ++k) dst[m][k] = *(const LAS bf16x8*)(lds + G_SA(b, h) + aoff + m * 2048 + k * 1024); } while (0)
; #define G_LDB(dst, b, h) do { _Pragma("unroll") for (int n = 0; n < 2; ++n) _Pragma("unroll") for (int k = 0; k < 2; ++k) dst[n][k] = *(const LAS bf16x8*)(lds + G_SB(b, h) + boff + n * 2048 + k * 1024); } while (0)
; #define G_WAIT_L(n) asm volatile("s_waitcnt lgkmcnt(" #n ")" ::: "memory")
; #define G_BAR __builtin_amdgcn_s_barrier()
; #define G_SCHED __builtin_amdgcn_sched_barrier(0)
; template <class Epi>
; __device__ __forceinline__ void gemm_phase(LAS unsigned char* lds, const bf16_t* Ag, const bf16_t* Btg, const int K, const int nM, const int nN, const Epi& E) {
;     ...
;         for (int t = 0; t < nt; t += 2) {
;             const bool last = (t == nt - 2);
;             const char* a1 = cA + (size_t)(t + 1) * kstep;
;             const char* a2 = last ? nA : cA + (size_t)(t + 2) * kstep; const char* b2 = last ? nB : cB + (size_t)(t + 2) * kstep;
;             const char* a3 = a2 + kstep; const char* b3 = b2 + kstep;
;             if (last && has_next && pmn != pm) E.prep(pmn, par ^ 1, lds);
;             G_LDB(B0, 0, 0); G_SCHED; G_LDA(At, 0, 0); G_STAGE(G_SA(1, 1), a1 + hstep);
;             G_WAIT_L(8); G_BAR; G_WAIT_L(0); G_MMA(0, 0, At, B0); G_BAR; G_SCHED;
;             G_LDB(B1, 0, 1); G_STAGE(G_SB(0, 0), b2);
;             G_BAR; G_WAIT_L(0); G_MMA(0, 1, At, B1); G_BAR;
;             G_LDA(At, 0, 1); G_STAGE(G_SA(0, 0), a2);
;             G_BAR; G_WAIT_L(0); G_MMA(1, 0, At, B0); G_BAR; G_SCHED;
;             G_STAGE(G_SB(0, 1), b2 + hstep);
.LBB0_848:
	s_add_u32 s26, s50, 0xfffc0080
	s_addc_u32 s54, s51, -1
	s_and_b64 s[52:53], s[52:53], exec
	s_cselect_b32 s55, s54, s25
	s_cselect_b32 s54, s26, s24
	s_cselect_b32 s53, s71, s14
	s_cselect_b32 s52, s70, s15
	ds_read_b128 v[130:133], v217
	ds_read_b128 v[134:137], v217 offset:1024
	ds_read_b128 v[144:147], v217 offset:2048
	ds_read_b128 v[148:151], v217 offset:3072
	s_add_i32 m0, s60, 0xc000
	ds_read_b128 v[156:159], v222
	ds_read_b128 v[160:163], v222 offset:1024
	ds_read_b128 v[164:167], v222 offset:2048
	ds_read_b128 v[180:183], v222 offset:3072
	ds_read_b128 v[184:187], v222 offset:4096
	ds_read_b128 v[224:227], v222 offset:5120
	ds_read_b128 v[228:231], v222 offset:6144
	global_load_lds_dwordx4 v170, s[50:51]
	s_add_i32 m0, s60, 0xe000
	ds_read_b128 v[232:235], v222 offset:7168
	global_load_lds_dwordx4 v168, s[50:51]
	s_waitcnt lgkmcnt(8)
	s_barrier
	s_waitcnt lgkmcnt(0)
	s_setprio 1
	s_waitcnt lgkmcnt(0)
	v_mfma_f32_16x16x32_bf16 v[152:155], v[130:133], v[156:159], v[152:155]
	v_mfma_f32_16x16x32_bf16 v[138:141], v[144:147], v[156:159], v[140:143]
	v_mfma_f32_16x16x32_bf16 v[116:119], v[130:133], v[164:167], v[116:119]
	v_mfma_f32_16x16x32_bf16 v[112:115], v[144:147], v[164:167], v[112:115]
	v_mfma_f32_16x16x32_bf16 v[100:103], v[130:133], v[184:187], v[100:103]
	v_mfma_f32_16x16x32_bf16 v[96:99], v[144:147], v[184:187], v[96:99]
	v_mfma_f32_16x16x32_bf16 v[84:87], v[130:133], v[228:231], v[84:87]
	v_mfma_f32_16x16x32_bf16 v[80:83], v[144:147], v[228:231], v[80:83]
	v_mfma_f32_16x16x32_bf16 v[152:155], v[134:137], v[160:163], v[152:155]
	v_mfma_f32_16x16x32_bf16 v[138:141], v[148:151], v[160:163], v[138:141]
	v_mfma_f32_16x16x32_bf16 v[116:119], v[134:137], v[180:183], v[116:119]
	v_mfma_f32_16x16x32_bf16 v[112:115], v[148:151], v[180:183], v[112:115]
	v_mfma_f32_16x16x32_bf16 v[100:103], v[134:137], v[224:227], v[100:103]
	v_mfma_f32_16x16x32_bf16 v[96:99], v[148:151], v[224:227], v[96:99]
	v_mfma_f32_16x16x32_bf16 v[84:87], v[134:137], v[232:235], v[84:87]
	v_mfma_f32_16x16x32_bf16 v[80:83], v[148:151], v[232:235], v[80:83]
	s_setprio 0
	s_barrier
	s_add_i32 s73, 0, 0x14000
	s_add_i32 m0, s59, 0x10000
	ds_read_b128 v[236:239], v217 offset:16384
	ds_read_b128 v[240:243], v217 offset:17408
	ds_read_b128 v[244:247], v217 offset:18432
	global_load_lds_dwordx4 v0, s[52:53]
	s_add_i32 m0, s59, 0x12000
	ds_read_b128 v[248:251], v217 offset:19456
	global_load_lds_dwordx4 v2, s[52:53]
	s_barrier
	s_waitcnt lgkmcnt(0)
	s_setprio 1
	s_waitcnt lgkmcnt(0)
	v_mfma_f32_16x16x32_bf16 v[124:127], v[236:239], v[156:159], v[124:127]
	v_mfma_f32_16x16x32_bf16 v[120:123], v[244:247], v[156:159], v[120:123]
	v_mfma_f32_16x16x32_bf16 v[108:111], v[236:239], v[164:167], v[108:111]
	v_mfma_f32_16x16x32_bf16 v[104:107], v[244:247], v[164:167], v[104:107]
	v_mfma_f32_16x16x32_bf16 v[92:95], v[236:239], v[184:187], v[92:95]
	v_mfma_f32_16x16x32_bf16 v[88:91], v[244:247], v[184:187], v[88:91]
	v_mfma_f32_16x16x32_bf16 v[76:79], v[236:239], v[228:231], v[76:79]
	v_mfma_f32_16x16x32_bf16 v[72:75], v[244:247], v[228:231], v[72:75]
	v_mfma_f32_16x16x32_bf16 v[124:127], v[240:243], v[160:163], v[124:127]
	v_mfma_f32_16x16x32_bf16 v[120:123], v[248:251], v[160:163], v[120:123]
	v_mfma_f32_16x16x32_bf16 v[108:111], v[240:243], v[180:183], v[108:111]
	v_mfma_f32_16x16x32_bf16 v[104:107], v[248:251], v[180:183], v[104:107]
	v_mfma_f32_16x16x32_bf16 v[92:95], v[240:243], v[224:227], v[92:95]
	v_mfma_f32_16x16x32_bf16 v[88:91], v[248:251], v[224:227], v[88:91]
	v_mfma_f32_16x16x32_bf16 v[76:79], v[240:243], v[232:235], v[76:79]
	v_mfma_f32_16x16x32_bf16 v[72:75], v[248:251], v[232:235], v[72:75]
	s_setprio 0
	s_mov_b32 m0, s60
	s_add_u32 s76, s54, 0x80
	s_addc_u32 s77, s55, 0
	s_barrier
	ds_read_b128 v[156:159], v222 offset:16384
	ds_read_b128 v[160:163], v222 offset:17408
	ds_read_b128 v[164:167], v222 offset:18432
	ds_read_b128 v[180:183], v222 offset:19456
	ds_read_b128 v[184:187], v222 offset:20480
	ds_read_b128 v[224:227], v222 offset:21504
	ds_read_b128 v[228:231], v222 offset:22528
	ds_read_b128 v[232:235], v222 offset:23552
	global_load_lds_dwordx4 v0, s[54:55]
	s_add_u32 s76, s54, 0x80
	s_mov_b32 m0, s61
	s_addc_u32 s77, s55, 0
	global_load_lds_dwordx4 v2, s[54:55]
	s_barrier
	s_waitcnt lgkmcnt(0)
	s_setprio 1
	s_waitcnt lgkmcnt(0)
	v_mfma_f32_16x16x32_bf16 v[60:63], v[130:133], v[156:159], v[60:63]
	v_mfma_f32_16x16x32_bf16 v[56:59], v[144:147], v[156:159], v[56:59]
	v_mfma_f32_16x16x32_bf16 v[44:47], v[130:133], v[164:167], v[44:47]
	v_mfma_f32_16x16x32_bf16 v[40:43], v[144:147], v[164:167], v[40:43]
	v_mfma_f32_16x16x32_bf16 v[28:31], v[130:133], v[184:187], v[28:31]
	v_mfma_f32_16x16x32_bf16 v[24:27], v[144:147], v[184:187], v[24:27]
	v_mfma_f32_16x16x32_bf16 v[12:15], v[130:133], v[228:231], v[12:15]
	v_mfma_f32_16x16x32_bf16 v[8:11], v[144:147], v[228:231], v[8:11]
	v_mfma_f32_16x16x32_bf16 v[60:63], v[134:137], v[160:163], v[60:63]
	v_mfma_f32_16x16x32_bf16 v[56:59], v[148:151], v[160:163], v[56:59]
	v_mfma_f32_16x16x32_bf16 v[44:47], v[134:137], v[180:183], v[44:47]
	v_mfma_f32_16x16x32_bf16 v[40:43], v[148:151], v[180:183], v[40:43]
	v_mfma_f32_16x16x32_bf16 v[28:31], v[134:137], v[224:227], v[28:31]
	v_mfma_f32_16x16x32_bf16 v[24:27], v[148:151], v[224:227], v[24:27]
	v_mfma_f32_16x16x32_bf16 v[12:15], v[134:137], v[232:235], v[12:15]
	v_mfma_f32_16x16x32_bf16 v[8:11], v[148:151], v[232:235], v[8:11]
	s_setprio 0
	s_barrier
	s_add_u32 s74, s52, 0x40000
	s_addc_u32 s75, s53, 0
	s_add_i32 m0, s59, 0x14000
	s_nop 0
	global_load_lds_dwordx4 v0, s[74:75]
	s_add_i32 m0, s59, 0x16000
	s_nop 0
	global_load_lds_dwordx4 v2, s[74:75]
	s_waitcnt vmcnt(6)
	s_barrier
; #define G_STAGE(bufoff, gbase) do { _Pragma("unroll") for (int _i = 0; _i < 2; ++_i) \
;         __builtin_amdgcn_global_load_lds((const unsigned*)((const char*)(gbase) + voff[_i]), (LAS unsigned*)(lds + (bufoff) + ldsw + _i * 8192), 16, 0, 0); } while (0)
; #define G_LDA(dst, b, h) do { _Pragma("unroll") for (int m = 0; m < 4; ++m) _Pragma("unroll") for (int k = 0; k < 2; ++k) dst[m][k] = *(const LAS bf16x8*)(lds + G_SA(b, h) + aoff + m * 2048 + k * 1024); } while (0)
; #define G_LDB(dst, b, h) do { _Pragma("unroll") for (int n = 0; n < 2; ++n) _Pragma("unroll") for (int k = 0; k < 2; ++k) dst[n][k] = *(const LAS bf16x8*)(lds + G_SB(b, h) + boff + n * 2048 + k * 1024); } while (0)
; #define G_MMA(ai, bj, At, Bt) do { __builtin_amdgcn_s_setprio(1); _Pragma("unroll") for (int m = 0; m < 4; ++m) _Pragma("unroll") for (int n = 0; n < 2; ++n) _Pragma("unroll") for (int k = 0; k < 2; ++k) \
;         acc[ai][bj][m][n] = MFMA16(Bt[n][k], At[m][k], acc[ai][bj][m][n]); __builtin_amdgcn_s_setprio(0); } while (0)
; #define G_WAIT_V(n) asm volatile("s_waitcnt vmcnt(" #n ")" ::: "memory")
; #define G_WAIT_L(n) asm volatile("s_waitcnt lgkmcnt(" #n ")" ::: "memory")
; #define G_BAR __builtin_amdgcn_s_barrier()
; #define G_SCHED __builtin_amdgcn_sched_barrier(0)
; template <class Epi>
; __device__ __forceinline__ void gemm_phase(LAS unsigned char* lds, const bf16_t* Ag, const bf16_t* Btg, const int K, const int nM, const int nN, const Epi& E) {
;     ...
;             G_WAIT_V(6); G_BAR; G_MMA(1, 1, At, B1); G_BAR;
;             G_LDB(B0, 1, 0); G_SCHED; G_LDA(At, 1, 0); G_STAGE(G_SA(0, 1), a2 + hstep);
;             G_WAIT_L(8); G_BAR; G_WAIT_L(0); G_MMA(0, 0, At, B0); G_BAR; G_SCHED;
;             G_LDB(B1, 1, 1); G_STAGE(G_SB(1, 0), b3);
	s_setprio 1
	v_mfma_f32_16x16x32_bf16 v[68:71], v[236:239], v[156:159], v[68:71]
	v_mfma_f32_16x16x32_bf16 v[64:67], v[244:247], v[156:159], v[64:67]
	v_mfma_f32_16x16x32_bf16 v[52:55], v[236:239], v[164:167], v[52:55]
	v_mfma_f32_16x16x32_bf16 v[48:51], v[244:247], v[164:167], v[48:51]
	v_mfma_f32_16x16x32_bf16 v[36:39], v[236:239], v[184:187], v[36:39]
	v_mfma_f32_16x16x32_bf16 v[32:35], v[244:247], v[184:187], v[32:35]
	v_mfma_f32_16x16x32_bf16 v[20:23], v[236:239], v[228:231], v[20:23]
	v_mfma_f32_16x16x32_bf16 v[16:19], v[244:247], v[228:231], v[16:19]
	v_mfma_f32_16x16x32_bf16 v[68:71], v[240:243], v[160:163], v[68:71]
	v_mfma_f32_16x16x32_bf16 v[64:67], v[248:251], v[160:163], v[64:67]
	v_mfma_f32_16x16x32_bf16 v[52:55], v[240:243], v[180:183], v[52:55]
	v_mfma_f32_16x16x32_bf16 v[48:51], v[248:251], v[180:183], v[48:51]
	v_mfma_f32_16x16x32_bf16 v[36:39], v[240:243], v[224:227], v[36:39]
	v_mfma_f32_16x16x32_bf16 v[32:35], v[248:251], v[224:227], v[32:35]
	v_mfma_f32_16x16x32_bf16 v[20:23], v[240:243], v[232:235], v[20:23]
	v_mfma_f32_16x16x32_bf16 v[16:19], v[248:251], v[232:235], v[16:19]
	s_setprio 0
	s_barrier
	ds_read_b128 v[130:133], v217 offset:32768
	ds_read_b128 v[134:137], v217 offset:33792
	ds_read_b128 v[144:147], v217 offset:34816
	ds_read_b128 v[148:151], v217 offset:35840
	s_add_u32 s54, s54, 0x40000
	s_addc_u32 s55, s55, 0
	s_mov_b32 m0, s62
	ds_read_b128 v[156:159], v222 offset:32768
	ds_read_b128 v[160:163], v222 offset:33792
	ds_read_b128 v[164:167], v222 offset:34816
	ds_read_b128 v[180:183], v222 offset:35840
	ds_read_b128 v[184:187], v222 offset:36864
	ds_read_b128 v[224:227], v222 offset:37888
	ds_read_b128 v[228:231], v222 offset:38912
	global_load_lds_dwordx4 v0, s[54:55]
	s_mov_b32 m0, s63
	ds_read_b128 v[232:235], v222 offset:39936
	global_load_lds_dwordx4 v2, s[54:55]
	s_waitcnt lgkmcnt(8)
	s_barrier
	s_waitcnt lgkmcnt(0)
	s_setprio 1
	s_waitcnt lgkmcnt(0)
	v_mfma_f32_16x16x32_bf16 v[152:155], v[130:133], v[156:159], v[152:155]
	v_mfma_f32_16x16x32_bf16 v[138:141], v[144:147], v[156:159], v[138:141]
	v_mfma_f32_16x16x32_bf16 v[116:119], v[130:133], v[164:167], v[116:119]
	v_mfma_f32_16x16x32_bf16 v[112:115], v[144:147], v[164:167], v[112:115]
	v_mfma_f32_16x16x32_bf16 v[100:103], v[130:133], v[184:187], v[100:103]
	v_mfma_f32_16x16x32_bf16 v[96:99], v[144:147], v[184:187], v[96:99]
	v_mfma_f32_16x16x32_bf16 v[84:87], v[130:133], v[228:231], v[84:87]
	v_mfma_f32_16x16x32_bf16 v[80:83], v[144:147], v[228:231], v[80:83]
	v_mfma_f32_16x16x32_bf16 v[152:155], v[134:137], v[160:163], v[152:155]
	v_mfma_f32_16x16x32_bf16 v[140:143], v[148:151], v[160:163], v[138:141]
	v_mfma_f32_16x16x32_bf16 v[116:119], v[134:137], v[180:183], v[116:119]
	v_mfma_f32_16x16x32_bf16 v[112:115], v[148:151], v[180:183], v[112:115]
	v_mfma_f32_16x16x32_bf16 v[100:103], v[134:137], v[224:227], v[100:103]
	v_mfma_f32_16x16x32_bf16 v[96:99], v[148:151], v[224:227], v[96:99]
	v_mfma_f32_16x16x32_bf16 v[84:87], v[134:137], v[232:235], v[84:87]
	v_mfma_f32_16x16x32_bf16 v[80:83], v[148:151], v[232:235], v[80:83]
	s_setprio 0
	s_barrier
	s_add_i32 s54, 0, 0x1c000
	s_add_i32 m0, s59, 0x18000
	ds_read_b128 v[236:239], v217 offset:49152
	ds_read_b128 v[240:243], v217 offset:50176
	ds_read_b128 v[244:247], v217 offset:51200
	ds_read_b128 v[248:251], v217 offset:52224
	s_add_u32 s98, s52, 0x80
	s_addc_u32 s99, s53, 0
	global_load_lds_dwordx4 v0, s[98:99]
	s_add_i32 m0, s59, 0x1a000
	s_nop 0
	global_load_lds_dwordx4 v2, s[98:99]
	s_barrier
; #define G_STAGE(bufoff, gbase) do { _Pragma("unroll") for (int _i = 0; _i < 2; ++_i) \
;         __builtin_amdgcn_global_load_lds((const unsigned*)((const char*)(gbase) + voff[_i]), (LAS unsigned*)(lds + (bufoff) + ldsw + _i * 8192), 16, 0, 0); } while (0)
; #define G_LDA(dst, b, h) do { _Pragma("unroll") for (int m = 0; m < 4; ++m) _Pragma("unroll") for (int k = 0; k < 2; ++k) dst[m][k] = *(const LAS bf16x8*)(lds + G_SA(b, h) + aoff + m * 2048 + k * 1024); } while (0)
; #define G_LDB(dst, b, h) do { _Pragma("unroll") for (int n = 0; n < 2; ++n) _Pragma("unroll") for (int k = 0; k < 2; ++k) dst[n][k] = *(const LAS bf16x8*)(lds + G_SB(b, h) + boff + n * 2048 + k * 1024); } while (0)
; #define G_MMA(ai, bj, At, Bt) do { __builtin_amdgcn_s_setprio(1); _Pragma("unroll") for (int m = 0; m < 4; ++m) _Pragma("unroll") for (int n = 0; n < 2; ++n) _Pragma("unroll") for (int k = 0; k < 2; ++k) \
;         acc[ai][bj][m][n] = MFMA16(Bt[n][k], At[m][k], acc[ai][bj][m][n]); __builtin_amdgcn_s_setprio(0); } while (0)
; #define G_WAIT_V(n) asm volatile("s_waitcnt vmcnt(" #n ")" ::: "memory")
; #define G_WAIT_L(n) asm volatile("s_waitcnt lgkmcnt(" #n ")" ::: "memory")
; #define G_BAR __builtin_amdgcn_s_barrier()
; #define G_SCHED __builtin_amdgcn_sched_barrier(0)
; template <class Epi>
; __device__ __forceinline__ void gemm_phase(LAS unsigned char* lds, const bf16_t* Ag, const bf16_t* Btg, const int K, const int nM, const int nN, const Epi& E) {
;     ...
;             G_LDB(B1, 1, 1); G_STAGE(G_SB(1, 0), b3);
;             G_BAR; G_WAIT_L(0); G_MMA(0, 1, At, B1); G_BAR;
;             G_LDA(At, 1, 1); G_STAGE(G_SA(1, 0), a3);
;             G_BAR; G_WAIT_L(0); G_MMA(1, 0, At, B0); G_BAR; G_SCHED;
;             G_STAGE(G_SB(1, 1), b3 + hstep);
;             G_WAIT_V(6); G_BAR; G_MMA(1, 1, At, B1); G_BAR;
	s_waitcnt lgkmcnt(0)
	s_setprio 1
	s_waitcnt lgkmcnt(0)
	v_mfma_f32_16x16x32_bf16 v[124:127], v[236:239], v[156:159], v[124:127]
	v_mfma_f32_16x16x32_bf16 v[120:123], v[244:247], v[156:159], v[120:123]
	v_mfma_f32_16x16x32_bf16 v[108:111], v[236:239], v[164:167], v[108:111]
	v_mfma_f32_16x16x32_bf16 v[104:107], v[244:247], v[164:167], v[104:107]
	v_mfma_f32_16x16x32_bf16 v[92:95], v[236:239], v[184:187], v[92:95]
	v_mfma_f32_16x16x32_bf16 v[88:91], v[244:247], v[184:187], v[88:91]
	v_mfma_f32_16x16x32_bf16 v[76:79], v[236:239], v[228:231], v[76:79]
	v_mfma_f32_16x16x32_bf16 v[72:75], v[244:247], v[228:231], v[72:75]
	v_mfma_f32_16x16x32_bf16 v[124:127], v[240:243], v[160:163], v[124:127]
	v_mfma_f32_16x16x32_bf16 v[120:123], v[248:251], v[160:163], v[120:123]
	v_mfma_f32_16x16x32_bf16 v[108:111], v[240:243], v[180:183], v[108:111]
	v_mfma_f32_16x16x32_bf16 v[104:107], v[248:251], v[180:183], v[104:107]
	v_mfma_f32_16x16x32_bf16 v[92:95], v[240:243], v[224:227], v[92:95]
	v_mfma_f32_16x16x32_bf16 v[88:91], v[248:251], v[224:227], v[88:91]
	v_mfma_f32_16x16x32_bf16 v[76:79], v[240:243], v[232:235], v[76:79]
	v_mfma_f32_16x16x32_bf16 v[72:75], v[248:251], v[232:235], v[72:75]
	s_setprio 0
	s_mov_b32 m0, s64
	s_barrier
	ds_read_b128 v[156:159], v222 offset:49152
	ds_read_b128 v[160:163], v222 offset:50176
	ds_read_b128 v[164:167], v222 offset:51200
	ds_read_b128 v[180:183], v222 offset:52224
	ds_read_b128 v[184:187], v222 offset:53248
	ds_read_b128 v[224:227], v222 offset:54272
	ds_read_b128 v[228:231], v222 offset:55296
	global_load_lds_dwordx4 v0, s[76:77]
	s_mov_b32 m0, s65
	ds_read_b128 v[232:235], v222 offset:56320
	global_load_lds_dwordx4 v2, s[76:77]
	s_barrier
	s_waitcnt lgkmcnt(0)
	s_setprio 1
	s_waitcnt lgkmcnt(0)
	v_mfma_f32_16x16x32_bf16 v[60:63], v[130:133], v[156:159], v[60:63]
	v_mfma_f32_16x16x32_bf16 v[56:59], v[144:147], v[156:159], v[56:59]
	v_mfma_f32_16x16x32_bf16 v[44:47], v[130:133], v[164:167], v[44:47]
	v_mfma_f32_16x16x32_bf16 v[40:43], v[144:147], v[164:167], v[40:43]
	v_mfma_f32_16x16x32_bf16 v[28:31], v[130:133], v[184:187], v[28:31]
	v_mfma_f32_16x16x32_bf16 v[24:27], v[144:147], v[184:187], v[24:27]
	v_mfma_f32_16x16x32_bf16 v[12:15], v[130:133], v[228:231], v[12:15]
	v_mfma_f32_16x16x32_bf16 v[8:11], v[144:147], v[228:231], v[8:11]
	v_mfma_f32_16x16x32_bf16 v[60:63], v[134:137], v[160:163], v[60:63]
	v_mfma_f32_16x16x32_bf16 v[56:59], v[148:151], v[160:163], v[56:59]
	v_mfma_f32_16x16x32_bf16 v[44:47], v[134:137], v[180:183], v[44:47]
	v_mfma_f32_16x16x32_bf16 v[40:43], v[148:151], v[180:183], v[40:43]
	v_mfma_f32_16x16x32_bf16 v[28:31], v[134:137], v[224:227], v[28:31]
	v_mfma_f32_16x16x32_bf16 v[24:27], v[148:151], v[224:227], v[24:27]
	v_mfma_f32_16x16x32_bf16 v[12:15], v[134:137], v[232:235], v[12:15]
	v_mfma_f32_16x16x32_bf16 v[8:11], v[148:151], v[232:235], v[8:11]
	s_setprio 0
	s_barrier
	s_add_u32 s52, s52, 0x40080
	s_addc_u32 s53, s53, 0
	s_add_i32 s26, s54, s59
	s_add_i32 m0, s59, 0x1c000
	s_nop 0
	global_load_lds_dwordx4 v0, s[52:53]
	s_add_i32 m0, s59, 0x1e000
	s_nop 0
	global_load_lds_dwordx4 v2, s[52:53]
	s_waitcnt vmcnt(6)
	s_barrier
	s_setprio 1
	v_mfma_f32_16x16x32_bf16 v[68:71], v[236:239], v[156:159], v[68:71]
	v_mfma_f32_16x16x32_bf16 v[64:67], v[244:247], v[156:159], v[64:67]
	v_mfma_f32_16x16x32_bf16 v[52:55], v[236:239], v[164:167], v[52:55]
	v_mfma_f32_16x16x32_bf16 v[48:51], v[244:247], v[164:167], v[48:51]
	v_mfma_f32_16x16x32_bf16 v[36:39], v[236:239], v[184:187], v[36:39]
	v_mfma_f32_16x16x32_bf16 v[32:35], v[244:247], v[184:187], v[32:35]
	v_mfma_f32_16x16x32_bf16 v[20:23], v[236:239], v[228:231], v[20:23]
	v_mfma_f32_16x16x32_bf16 v[16:19], v[244:247], v[228:231], v[16:19]
	v_mfma_f32_16x16x32_bf16 v[68:71], v[240:243], v[160:163], v[68:71]
	v_mfma_f32_16x16x32_bf16 v[64:67], v[248:251], v[160:163], v[64:67]
	v_mfma_f32_16x16x32_bf16 v[52:55], v[240:243], v[180:183], v[52:55]
	v_mfma_f32_16x16x32_bf16 v[48:51], v[248:251], v[180:183], v[48:51]
	v_mfma_f32_16x16x32_bf16 v[36:39], v[240:243], v[224:227], v[36:39]
	v_mfma_f32_16x16x32_bf16 v[32:35], v[248:251], v[224:227], v[32:35]
	v_mfma_f32_16x16x32_bf16 v[20:23], v[240:243], v[232:235], v[20:23]
	v_mfma_f32_16x16x32_bf16 v[16:19], v[248:251], v[232:235], v[16:19]
	s_setprio 0
	s_add_i32 s72, s72, 2
	s_add_u32 s70, s70, 0x100
	s_addc_u32 s71, s71, 0
	s_add_u32 s50, s50, 0x100
	s_addc_u32 s51, s51, 0
	s_cmp_gt_u32 s72, 13
	s_barrier
	s_cbranch_scc1 .LBB0_852
